# resid phases: DMA prologue issued before the X/gate prefetch loads
# speedup vs baseline: 1.0033x; 1.0033x over previous
.Lr6_tile:
	s_cmp_lt_u32 s15, 0x200
	s_cbranch_scc0 .Lr6_end
	s_and_b32 s2, s15, 63
	s_lshr_b32 s3, s15, 6
	s_mul_i32 s14, s2, 0x80000
	s_add_u32 s8, s26, s14
	s_addc_u32 s9, s27, 0
	s_mul_i32 s14, s3, 0x80000
	s_add_u32 s10, s28, s14
	s_addc_u32 s11, s29, 0
	s_lshl_b32 s14, s2, 19
	s_lshl_b32 s6, s3, 9
	s_add_u32 s14, s14, s6
	s_add_u32 s20, s4, 0x6b7a100
	s_addc_u32 s21, s5, 0
	s_add_u32 s20, s20, s14
	s_addc_u32 s21, s21, 0
	s_sub_u32 s7, s2, 32
	s_lshr_b32 s7, s7, 3
	s_add_u32 s7, s7, 1
	s_cmp_lt_u32 s2, 32
	s_cselect_b32 s7, 0, s7
	s_mul_i32 s7, s7, 0x6000
	s_add_u32 s7, s7, s6
	s_add_u32 s22, s4, 0x6b04000
	s_addc_u32 s23, s5, 0
	s_add_u32 s22, s22, s7
	s_addc_u32 s23, s23, 0
	v_readfirstlane_b32 s12, v247
	s_lshl_b32 s12, s12, 12
	s_add_u32 m0, s12, 0x0
	v_mov_b32_e32 v0, 0
	global_load_lds_dwordx4 v248, s[8:9]
	v_mov_b32_e32 v1, 0
	s_add_u32 m0, s12, 0x400
	v_mov_b32_e32 v2, 0
	global_load_lds_dwordx4 v249, s[8:9]
	v_mov_b32_e32 v3, 0
	s_add_u32 m0, s12, 0x800
	v_mov_b32_e32 v4, 0
	global_load_lds_dwordx4 v250, s[8:9]
	v_mov_b32_e32 v5, 0
	s_add_u32 m0, s12, 0xc00
	v_mov_b32_e32 v6, 0
	global_load_lds_dwordx4 v251, s[8:9]
	v_mov_b32_e32 v7, 0
	s_add_u32 m0, s12, 0x8000
	v_mov_b32_e32 v8, 0
	global_load_lds_dwordx4 v248, s[10:11]
	v_mov_b32_e32 v9, 0
	s_add_u32 m0, s12, 0x8400
	v_mov_b32_e32 v10, 0
	global_load_lds_dwordx4 v249, s[10:11]
	v_mov_b32_e32 v11, 0
	s_add_u32 m0, s12, 0x8800
	v_mov_b32_e32 v12, 0
	global_load_lds_dwordx4 v250, s[10:11]
	v_mov_b32_e32 v13, 0
	s_add_u32 m0, s12, 0x8c00
	v_mov_b32_e32 v14, 0
	global_load_lds_dwordx4 v251, s[10:11]
	v_mov_b32_e32 v15, 0
	s_add_u32 s8, s8, 0x80
	s_addc_u32 s9, s9, 0
	s_add_u32 s10, s10, 0x80
	s_addc_u32 s11, s11, 0
	s_add_u32 m0, s12, 0x4000
	v_mov_b32_e32 v16, 0
	global_load_lds_dwordx4 v248, s[8:9]
	v_mov_b32_e32 v17, 0
	s_add_u32 m0, s12, 0x4400
	v_mov_b32_e32 v18, 0
	global_load_lds_dwordx4 v249, s[8:9]
	v_mov_b32_e32 v19, 0
	s_add_u32 m0, s12, 0x4800
	v_mov_b32_e32 v20, 0
	global_load_lds_dwordx4 v250, s[8:9]
	v_mov_b32_e32 v21, 0
	s_add_u32 m0, s12, 0x4c00
	v_mov_b32_e32 v22, 0
	global_load_lds_dwordx4 v251, s[8:9]
	v_mov_b32_e32 v23, 0
	s_add_u32 m0, s12, 0xc000
	v_mov_b32_e32 v24, 0
	global_load_lds_dwordx4 v248, s[10:11]
	v_mov_b32_e32 v25, 0
	s_add_u32 m0, s12, 0xc400
	v_mov_b32_e32 v26, 0
	global_load_lds_dwordx4 v249, s[10:11]
	v_mov_b32_e32 v27, 0
	s_add_u32 m0, s12, 0xc800
	v_mov_b32_e32 v28, 0
	global_load_lds_dwordx4 v250, s[10:11]
	v_mov_b32_e32 v29, 0
	s_add_u32 m0, s12, 0xcc00
	v_mov_b32_e32 v30, 0
	global_load_lds_dwordx4 v251, s[10:11]
	v_mov_b32_e32 v31, 0
	s_add_u32 s8, s8, 0x80
	s_addc_u32 s9, s9, 0
	s_add_u32 s10, s10, 0x80
	s_addc_u32 s11, s11, 0
	v_mov_b32_e32 v32, 0
	v_mov_b32_e32 v33, 0
	v_mov_b32_e32 v34, 0
	v_mov_b32_e32 v35, 0
	v_mov_b32_e32 v36, 0
	v_mov_b32_e32 v37, 0
	v_mov_b32_e32 v38, 0
	v_mov_b32_e32 v39, 0
	v_mov_b32_e32 v40, 0
	v_mov_b32_e32 v41, 0
	v_mov_b32_e32 v42, 0
	v_mov_b32_e32 v43, 0
	v_mov_b32_e32 v44, 0
	v_mov_b32_e32 v45, 0
	v_mov_b32_e32 v46, 0
	v_mov_b32_e32 v47, 0
	v_mov_b32_e32 v48, 0
	v_mov_b32_e32 v49, 0
	v_mov_b32_e32 v50, 0
	v_mov_b32_e32 v51, 0
	v_mov_b32_e32 v52, 0
	v_mov_b32_e32 v53, 0
	v_mov_b32_e32 v54, 0
	v_mov_b32_e32 v55, 0
	v_mov_b32_e32 v56, 0
	v_mov_b32_e32 v57, 0
	v_mov_b32_e32 v58, 0
	v_mov_b32_e32 v59, 0
	v_mov_b32_e32 v60, 0
	v_mov_b32_e32 v61, 0
	v_mov_b32_e32 v62, 0
	v_mov_b32_e32 v63, 0
	global_load_dword v201, v245, s[22:23] offset:0
	global_load_dword v202, v245, s[22:23] offset:64
	global_load_dword v203, v245, s[22:23] offset:128
	global_load_dword v204, v245, s[22:23] offset:192
	s_load_dwordx4 s[36:39], s[0:1], 0x0
	s_sub_u32 s7, s2, 32
	s_cmp_lt_u32 s2, 32
	s_cselect_b32 s7, s2, s7
	s_lshl_b32 s7, s7, 19
	s_add_u32 s7, s7, s6
	s_waitcnt lgkmcnt(0)
	s_cmp_lt_u32 s2, 32
	s_cselect_b32 s18, s36, s38
	s_cselect_b32 s19, s37, s39
	s_add_u32 s18, s18, s7
	s_addc_u32 s19, s19, 0
	global_load_dword v129, v246, s[18:19] offset:0
	global_load_dword v130, v246, s[18:19] offset:64
	global_load_dword v131, v246, s[18:19] offset:128
	global_load_dword v132, v246, s[18:19] offset:192
	s_add_u32 s18, s18, 0x1000
	s_addc_u32 s19, s19, 0
	global_load_dword v133, v246, s[18:19] offset:0
	global_load_dword v134, v246, s[18:19] offset:64
	global_load_dword v135, v246, s[18:19] offset:128
	global_load_dword v136, v246, s[18:19] offset:192
	s_add_u32 s18, s18, 0x1000
	s_addc_u32 s19, s19, 0
	global_load_dword v137, v246, s[18:19] offset:0
	global_load_dword v138, v246, s[18:19] offset:64
	global_load_dword v139, v246, s[18:19] offset:128
	global_load_dword v140, v246, s[18:19] offset:192
	s_add_u32 s18, s18, 0x1000
	s_addc_u32 s19, s19, 0
	global_load_dword v141, v246, s[18:19] offset:0
	global_load_dword v142, v246, s[18:19] offset:64
	global_load_dword v143, v246, s[18:19] offset:128
	global_load_dword v144, v246, s[18:19] offset:192
	s_add_u32 s18, s18, 0xd000
	s_addc_u32 s19, s19, 0
	global_load_dword v145, v246, s[18:19] offset:0
	global_load_dword v146, v246, s[18:19] offset:64
	global_load_dword v147, v246, s[18:19] offset:128
	global_load_dword v148, v246, s[18:19] offset:192
	s_add_u32 s18, s18, 0x1000
	s_addc_u32 s19, s19, 0
	global_load_dword v149, v246, s[18:19] offset:0
	global_load_dword v150, v246, s[18:19] offset:64
	global_load_dword v151, v246, s[18:19] offset:128
	global_load_dword v152, v246, s[18:19] offset:192
	s_add_u32 s18, s18, 0x1000
	s_addc_u32 s19, s19, 0
	global_load_dword v153, v246, s[18:19] offset:0
	global_load_dword v154, v246, s[18:19] offset:64
	global_load_dword v155, v246, s[18:19] offset:128
	global_load_dword v156, v246, s[18:19] offset:192
	s_add_u32 s18, s18, 0x1000
	s_addc_u32 s19, s19, 0
	global_load_dword v157, v246, s[18:19] offset:0
	global_load_dword v158, v246, s[18:19] offset:64
	global_load_dword v159, v246, s[18:19] offset:128
	global_load_dword v160, v246, s[18:19] offset:192
	s_add_u32 s18, s18, 0xd000
	s_addc_u32 s19, s19, 0
	global_load_dword v161, v246, s[18:19] offset:0
	global_load_dword v170, v246, s[18:19] offset:64
	global_load_dword v171, v246, s[18:19] offset:128
	global_load_dword v172, v246, s[18:19] offset:192
	s_add_u32 s18, s18, 0x1000
	s_addc_u32 s19, s19, 0
	global_load_dword v173, v246, s[18:19] offset:0
	global_load_dword v174, v246, s[18:19] offset:64
	global_load_dword v175, v246, s[18:19] offset:128
	global_load_dword v176, v246, s[18:19] offset:192
	s_add_u32 s18, s18, 0x1000
	s_addc_u32 s19, s19, 0
	global_load_dword v177, v246, s[18:19] offset:0
	global_load_dword v178, v246, s[18:19] offset:64
	global_load_dword v179, v246, s[18:19] offset:128
	global_load_dword v180, v246, s[18:19] offset:192
	s_add_u32 s18, s18, 0x1000
	s_addc_u32 s19, s19, 0
	global_load_dword v181, v246, s[18:19] offset:0
	global_load_dword v182, v246, s[18:19] offset:64
	global_load_dword v183, v246, s[18:19] offset:128
	global_load_dword v184, v246, s[18:19] offset:192
	s_add_u32 s18, s18, 0xd000
	s_addc_u32 s19, s19, 0
	global_load_dword v185, v246, s[18:19] offset:0
	global_load_dword v186, v246, s[18:19] offset:64
	global_load_dword v187, v246, s[18:19] offset:128
	global_load_dword v188, v246, s[18:19] offset:192
	s_add_u32 s18, s18, 0x1000
	s_addc_u32 s19, s19, 0
	global_load_dword v189, v246, s[18:19] offset:0
	global_load_dword v190, v246, s[18:19] offset:64
	global_load_dword v191, v246, s[18:19] offset:128
	global_load_dword v192, v246, s[18:19] offset:192
	s_add_u32 s18, s18, 0x1000
	s_addc_u32 s19, s19, 0
	global_load_dword v193, v246, s[18:19] offset:0
	global_load_dword v194, v246, s[18:19] offset:64
	global_load_dword v195, v246, s[18:19] offset:128
	global_load_dword v196, v246, s[18:19] offset:192
	s_add_u32 s18, s18, 0x1000
	s_addc_u32 s19, s19, 0
	global_load_dword v197, v246, s[18:19] offset:0
	global_load_dword v198, v246, s[18:19] offset:64
	global_load_dword v199, v246, s[18:19] offset:128
	global_load_dword v200, v246, s[18:19] offset:192
	s_waitcnt vmcnt(63)
	s_barrier
	ds_read_b128 v[64:67], v252 offset:0
	ds_read_b128 v[96:99], v254 offset:32768
	ds_read_b128 v[100:103], v254 offset:34816
	ds_read_b128 v[104:107], v254 offset:36864
	ds_read_b128 v[108:111], v254 offset:38912
	ds_read_b128 v[68:71], v252 offset:2048
	ds_read_b128 v[72:75], v252 offset:4096
	ds_read_b128 v[76:79], v252 offset:6144
	ds_read_b128 v[80:83], v253 offset:0
	ds_read_b128 v[112:115], v255 offset:32768
	ds_read_b128 v[116:119], v255 offset:34816
	ds_read_b128 v[120:123], v255 offset:36864
	ds_read_b128 v[124:127], v255 offset:38912
	s_waitcnt lgkmcnt(11)
	v_mfma_f32_16x16x32_bf16 v[0:3], v[64:67], v[96:99], v[0:3]
	s_waitcnt lgkmcnt(10)
	v_mfma_f32_16x16x32_bf16 v[4:7], v[64:67], v[100:103], v[4:7]
	s_waitcnt lgkmcnt(9)
	v_mfma_f32_16x16x32_bf16 v[8:11], v[64:67], v[104:107], v[8:11]
	s_waitcnt lgkmcnt(8)
	v_mfma_f32_16x16x32_bf16 v[12:15], v[64:67], v[108:111], v[12:15]
	ds_read_b128 v[84:87], v253 offset:2048
	ds_read_b128 v[88:91], v253 offset:4096
	ds_read_b128 v[92:95], v253 offset:6144
	s_waitcnt lgkmcnt(10)
	v_mfma_f32_16x16x32_bf16 v[16:19], v[68:71], v[96:99], v[16:19]
	v_mfma_f32_16x16x32_bf16 v[20:23], v[68:71], v[100:103], v[20:23]
	v_mfma_f32_16x16x32_bf16 v[24:27], v[68:71], v[104:107], v[24:27]
	v_mfma_f32_16x16x32_bf16 v[28:31], v[68:71], v[108:111], v[28:31]
	s_waitcnt lgkmcnt(0)
	s_barrier
	s_add_u32 m0, s12, 0x0
	v_mfma_f32_16x16x32_bf16 v[32:35], v[72:75], v[96:99], v[32:35]
	global_load_lds_dwordx4 v248, s[8:9]
	s_add_u32 m0, s12, 0x400
	v_mfma_f32_16x16x32_bf16 v[36:39], v[72:75], v[100:103], v[36:39]
	global_load_lds_dwordx4 v249, s[8:9]
	s_add_u32 m0, s12, 0x800
	v_mfma_f32_16x16x32_bf16 v[40:43], v[72:75], v[104:107], v[40:43]
	global_load_lds_dwordx4 v250, s[8:9]
	s_add_u32 m0, s12, 0xc00
	v_mfma_f32_16x16x32_bf16 v[44:47], v[72:75], v[108:111], v[44:47]
	global_load_lds_dwordx4 v251, s[8:9]
	s_add_u32 m0, s12, 0x8000
	v_mfma_f32_16x16x32_bf16 v[48:51], v[76:79], v[96:99], v[48:51]
	global_load_lds_dwordx4 v248, s[10:11]
	s_add_u32 m0, s12, 0x8400
	v_mfma_f32_16x16x32_bf16 v[52:55], v[76:79], v[100:103], v[52:55]
	global_load_lds_dwordx4 v249, s[10:11]
	s_add_u32 m0, s12, 0x8800
	v_mfma_f32_16x16x32_bf16 v[56:59], v[76:79], v[104:107], v[56:59]
	global_load_lds_dwordx4 v250, s[10:11]
	s_add_u32 m0, s12, 0x8c00
	v_mfma_f32_16x16x32_bf16 v[60:63], v[76:79], v[108:111], v[60:63]
	global_load_lds_dwordx4 v251, s[10:11]
	s_add_u32 s8, s8, 0x80
	s_addc_u32 s9, s9, 0
	s_add_u32 s10, s10, 0x80
	s_addc_u32 s11, s11, 0
	s_waitcnt vmcnt(63)
	s_barrier
	ds_read_b128 v[64:67], v252 offset:16384
	ds_read_b128 v[96:99], v254 offset:49152
	ds_read_b128 v[100:103], v254 offset:51200
	ds_read_b128 v[104:107], v254 offset:53248
	ds_read_b128 v[108:111], v254 offset:55296
	ds_read_b128 v[68:71], v252 offset:18432
	ds_read_b128 v[72:75], v252 offset:20480
	ds_read_b128 v[76:79], v252 offset:22528
	v_mfma_f32_16x16x32_bf16 v[0:3], v[80:83], v[112:115], v[0:3]
	v_mfma_f32_16x16x32_bf16 v[4:7], v[80:83], v[116:119], v[4:7]
	v_mfma_f32_16x16x32_bf16 v[8:11], v[80:83], v[120:123], v[8:11]
	v_mfma_f32_16x16x32_bf16 v[12:15], v[80:83], v[124:127], v[12:15]
	v_mfma_f32_16x16x32_bf16 v[16:19], v[84:87], v[112:115], v[16:19]
	v_mfma_f32_16x16x32_bf16 v[20:23], v[84:87], v[116:119], v[20:23]
	v_mfma_f32_16x16x32_bf16 v[24:27], v[84:87], v[120:123], v[24:27]
	v_mfma_f32_16x16x32_bf16 v[28:31], v[84:87], v[124:127], v[28:31]
	v_mfma_f32_16x16x32_bf16 v[32:35], v[88:91], v[112:115], v[32:35]
	v_mfma_f32_16x16x32_bf16 v[36:39], v[88:91], v[116:119], v[36:39]
	v_mfma_f32_16x16x32_bf16 v[40:43], v[88:91], v[120:123], v[40:43]
	v_mfma_f32_16x16x32_bf16 v[44:47], v[88:91], v[124:127], v[44:47]
	v_mfma_f32_16x16x32_bf16 v[48:51], v[92:95], v[112:115], v[48:51]
	v_mfma_f32_16x16x32_bf16 v[52:55], v[92:95], v[116:119], v[52:55]
	v_mfma_f32_16x16x32_bf16 v[56:59], v[92:95], v[120:123], v[56:59]
	v_mfma_f32_16x16x32_bf16 v[60:63], v[92:95], v[124:127], v[60:63]
	ds_read_b128 v[80:83], v253 offset:16384
	ds_read_b128 v[112:115], v255 offset:49152
	ds_read_b128 v[116:119], v255 offset:51200
	ds_read_b128 v[120:123], v255 offset:53248
	ds_read_b128 v[124:127], v255 offset:55296
	ds_read_b128 v[84:87], v253 offset:18432
	ds_read_b128 v[88:91], v253 offset:20480
	ds_read_b128 v[92:95], v253 offset:22528
	s_waitcnt lgkmcnt(14)
	v_mfma_f32_16x16x32_bf16 v[0:3], v[64:67], v[96:99], v[0:3]
	s_waitcnt lgkmcnt(13)
	v_mfma_f32_16x16x32_bf16 v[4:7], v[64:67], v[100:103], v[4:7]
	s_waitcnt lgkmcnt(12)
	v_mfma_f32_16x16x32_bf16 v[8:11], v[64:67], v[104:107], v[8:11]
	s_waitcnt lgkmcnt(11)
	v_mfma_f32_16x16x32_bf16 v[12:15], v[64:67], v[108:111], v[12:15]
	s_waitcnt lgkmcnt(10)
	v_mfma_f32_16x16x32_bf16 v[16:19], v[68:71], v[96:99], v[16:19]
	v_mfma_f32_16x16x32_bf16 v[20:23], v[68:71], v[100:103], v[20:23]
	v_mfma_f32_16x16x32_bf16 v[24:27], v[68:71], v[104:107], v[24:27]
	v_mfma_f32_16x16x32_bf16 v[28:31], v[68:71], v[108:111], v[28:31]
	s_waitcnt lgkmcnt(0)
	s_barrier
	s_add_u32 m0, s12, 0x4000
	v_mfma_f32_16x16x32_bf16 v[32:35], v[72:75], v[96:99], v[32:35]
	global_load_lds_dwordx4 v248, s[8:9]
	s_add_u32 m0, s12, 0x4400
	v_mfma_f32_16x16x32_bf16 v[36:39], v[72:75], v[100:103], v[36:39]
	global_load_lds_dwordx4 v249, s[8:9]
	s_add_u32 m0, s12, 0x4800
	v_mfma_f32_16x16x32_bf16 v[40:43], v[72:75], v[104:107], v[40:43]
	global_load_lds_dwordx4 v250, s[8:9]
	s_add_u32 m0, s12, 0x4c00
	v_mfma_f32_16x16x32_bf16 v[44:47], v[72:75], v[108:111], v[44:47]
	global_load_lds_dwordx4 v251, s[8:9]
	s_add_u32 m0, s12, 0xc000
	v_mfma_f32_16x16x32_bf16 v[48:51], v[76:79], v[96:99], v[48:51]
	global_load_lds_dwordx4 v248, s[10:11]
	s_add_u32 m0, s12, 0xc400
	v_mfma_f32_16x16x32_bf16 v[52:55], v[76:79], v[100:103], v[52:55]
	global_load_lds_dwordx4 v249, s[10:11]
	s_add_u32 m0, s12, 0xc800
	v_mfma_f32_16x16x32_bf16 v[56:59], v[76:79], v[104:107], v[56:59]
	global_load_lds_dwordx4 v250, s[10:11]
	s_add_u32 m0, s12, 0xcc00
	v_mfma_f32_16x16x32_bf16 v[60:63], v[76:79], v[108:111], v[60:63]
	global_load_lds_dwordx4 v251, s[10:11]
	s_add_u32 s8, s8, 0x80
	s_addc_u32 s9, s9, 0
	s_add_u32 s10, s10, 0x80
	s_addc_u32 s11, s11, 0
	s_mov_b32 s13, 14

.Lr9_tile:
	s_cmp_lt_u32 s15, 0x200
	s_cbranch_scc0 .Lr9_end
	s_and_b32 s2, s15, 63
	s_lshr_b32 s3, s15, 6
	s_mul_i32 s14, s2, 0xb0000
	s_add_u32 s8, s26, s14
	s_addc_u32 s9, s27, 0
	s_mul_i32 s14, s3, 0xb0000
	s_add_u32 s10, s28, s14
	s_addc_u32 s11, s29, 0
	s_lshl_b32 s14, s2, 19
	s_lshl_b32 s6, s3, 9
	s_add_u32 s14, s14, s6
	s_add_u32 s20, s4, 0x6b7a100
	s_addc_u32 s21, s5, 0
	s_add_u32 s20, s20, s14
	s_addc_u32 s21, s21, 0
	s_sub_u32 s7, s2, 32
	s_lshr_b32 s7, s7, 3
	s_add_u32 s7, s7, 1
	s_cmp_lt_u32 s2, 32
	s_cselect_b32 s7, 0, s7
	s_mul_i32 s7, s7, 0x6000
	s_add_u32 s7, s7, s6
	s_add_u32 s22, s4, 0x6b07000
	s_addc_u32 s23, s5, 0
	s_add_u32 s22, s22, s7
	s_addc_u32 s23, s23, 0
	v_readfirstlane_b32 s12, v247
	s_lshl_b32 s12, s12, 12
	s_add_u32 m0, s12, 0x0
	v_mov_b32_e32 v0, 0
	global_load_lds_dwordx4 v248, s[8:9]
	v_mov_b32_e32 v1, 0
	s_add_u32 m0, s12, 0x400
	v_mov_b32_e32 v2, 0
	global_load_lds_dwordx4 v249, s[8:9]
	v_mov_b32_e32 v3, 0
	s_add_u32 m0, s12, 0x800
	v_mov_b32_e32 v4, 0
	global_load_lds_dwordx4 v250, s[8:9]
	v_mov_b32_e32 v5, 0
	s_add_u32 m0, s12, 0xc00
	v_mov_b32_e32 v6, 0
	global_load_lds_dwordx4 v251, s[8:9]
	v_mov_b32_e32 v7, 0
	s_add_u32 m0, s12, 0x8000
	v_mov_b32_e32 v8, 0
	global_load_lds_dwordx4 v248, s[10:11]
	v_mov_b32_e32 v9, 0
	s_add_u32 m0, s12, 0x8400
	v_mov_b32_e32 v10, 0
	global_load_lds_dwordx4 v249, s[10:11]
	v_mov_b32_e32 v11, 0
	s_add_u32 m0, s12, 0x8800
	v_mov_b32_e32 v12, 0
	global_load_lds_dwordx4 v250, s[10:11]
	v_mov_b32_e32 v13, 0
	s_add_u32 m0, s12, 0x8c00
	v_mov_b32_e32 v14, 0
	global_load_lds_dwordx4 v251, s[10:11]
	v_mov_b32_e32 v15, 0
	s_add_u32 s8, s8, 0x80
	s_addc_u32 s9, s9, 0
	s_add_u32 s10, s10, 0x80
	s_addc_u32 s11, s11, 0
	s_add_u32 m0, s12, 0x4000
	v_mov_b32_e32 v16, 0
	global_load_lds_dwordx4 v248, s[8:9]
	v_mov_b32_e32 v17, 0
	s_add_u32 m0, s12, 0x4400
	v_mov_b32_e32 v18, 0
	global_load_lds_dwordx4 v249, s[8:9]
	v_mov_b32_e32 v19, 0
	s_add_u32 m0, s12, 0x4800
	v_mov_b32_e32 v20, 0
	global_load_lds_dwordx4 v250, s[8:9]
	v_mov_b32_e32 v21, 0
	s_add_u32 m0, s12, 0x4c00
	v_mov_b32_e32 v22, 0
	global_load_lds_dwordx4 v251, s[8:9]
	v_mov_b32_e32 v23, 0
	s_add_u32 m0, s12, 0xc000
	v_mov_b32_e32 v24, 0
	global_load_lds_dwordx4 v248, s[10:11]
	v_mov_b32_e32 v25, 0
	s_add_u32 m0, s12, 0xc400
	v_mov_b32_e32 v26, 0
	global_load_lds_dwordx4 v249, s[10:11]
	v_mov_b32_e32 v27, 0
	s_add_u32 m0, s12, 0xc800
	v_mov_b32_e32 v28, 0
	global_load_lds_dwordx4 v250, s[10:11]
	v_mov_b32_e32 v29, 0
	s_add_u32 m0, s12, 0xcc00
	v_mov_b32_e32 v30, 0
	global_load_lds_dwordx4 v251, s[10:11]
	v_mov_b32_e32 v31, 0
	s_add_u32 s8, s8, 0x80
	s_addc_u32 s9, s9, 0
	s_add_u32 s10, s10, 0x80
	s_addc_u32 s11, s11, 0
	v_mov_b32_e32 v32, 0
	v_mov_b32_e32 v33, 0
	v_mov_b32_e32 v34, 0
	v_mov_b32_e32 v35, 0
	v_mov_b32_e32 v36, 0
	v_mov_b32_e32 v37, 0
	v_mov_b32_e32 v38, 0
	v_mov_b32_e32 v39, 0
	v_mov_b32_e32 v40, 0
	v_mov_b32_e32 v41, 0
	v_mov_b32_e32 v42, 0
	v_mov_b32_e32 v43, 0
	v_mov_b32_e32 v44, 0
	v_mov_b32_e32 v45, 0
	v_mov_b32_e32 v46, 0
	v_mov_b32_e32 v47, 0
	v_mov_b32_e32 v48, 0
	v_mov_b32_e32 v49, 0
	v_mov_b32_e32 v50, 0
	v_mov_b32_e32 v51, 0
	v_mov_b32_e32 v52, 0
	v_mov_b32_e32 v53, 0
	v_mov_b32_e32 v54, 0
	v_mov_b32_e32 v55, 0
	v_mov_b32_e32 v56, 0
	v_mov_b32_e32 v57, 0
	v_mov_b32_e32 v58, 0
	v_mov_b32_e32 v59, 0
	v_mov_b32_e32 v60, 0
	v_mov_b32_e32 v61, 0
	v_mov_b32_e32 v62, 0
	v_mov_b32_e32 v63, 0
	global_load_dword v201, v245, s[22:23] offset:0
	global_load_dword v202, v245, s[22:23] offset:64
	global_load_dword v203, v245, s[22:23] offset:128
	global_load_dword v204, v245, s[22:23] offset:192
	s_mov_b64 s[18:19], s[20:21]
	global_load_dword v129, v246, s[18:19] offset:0
	global_load_dword v130, v246, s[18:19] offset:64
	global_load_dword v131, v246, s[18:19] offset:128
	global_load_dword v132, v246, s[18:19] offset:192
	s_add_u32 s18, s18, 0x1000
	s_addc_u32 s19, s19, 0
	global_load_dword v133, v246, s[18:19] offset:0
	global_load_dword v134, v246, s[18:19] offset:64
	global_load_dword v135, v246, s[18:19] offset:128
	global_load_dword v136, v246, s[18:19] offset:192
	s_add_u32 s18, s18, 0x1000
	s_addc_u32 s19, s19, 0
	global_load_dword v137, v246, s[18:19] offset:0
	global_load_dword v138, v246, s[18:19] offset:64
	global_load_dword v139, v246, s[18:19] offset:128
	global_load_dword v140, v246, s[18:19] offset:192
	s_add_u32 s18, s18, 0x1000
	s_addc_u32 s19, s19, 0
	global_load_dword v141, v246, s[18:19] offset:0
	global_load_dword v142, v246, s[18:19] offset:64
	global_load_dword v143, v246, s[18:19] offset:128
	global_load_dword v144, v246, s[18:19] offset:192
	s_add_u32 s18, s18, 0xd000
	s_addc_u32 s19, s19, 0
	global_load_dword v145, v246, s[18:19] offset:0
	global_load_dword v146, v246, s[18:19] offset:64
	global_load_dword v147, v246, s[18:19] offset:128
	global_load_dword v148, v246, s[18:19] offset:192
	s_add_u32 s18, s18, 0x1000
	s_addc_u32 s19, s19, 0
	global_load_dword v149, v246, s[18:19] offset:0
	global_load_dword v150, v246, s[18:19] offset:64
	global_load_dword v151, v246, s[18:19] offset:128
	global_load_dword v152, v246, s[18:19] offset:192
	s_add_u32 s18, s18, 0x1000
	s_addc_u32 s19, s19, 0
	global_load_dword v153, v246, s[18:19] offset:0
	global_load_dword v154, v246, s[18:19] offset:64
	global_load_dword v155, v246, s[18:19] offset:128
	global_load_dword v156, v246, s[18:19] offset:192
	s_add_u32 s18, s18, 0x1000
	s_addc_u32 s19, s19, 0
	global_load_dword v157, v246, s[18:19] offset:0
	global_load_dword v158, v246, s[18:19] offset:64
	global_load_dword v159, v246, s[18:19] offset:128
	global_load_dword v160, v246, s[18:19] offset:192
	s_add_u32 s18, s18, 0xd000
	s_addc_u32 s19, s19, 0
	global_load_dword v161, v246, s[18:19] offset:0
	global_load_dword v170, v246, s[18:19] offset:64
	global_load_dword v171, v246, s[18:19] offset:128
	global_load_dword v172, v246, s[18:19] offset:192
	s_add_u32 s18, s18, 0x1000
	s_addc_u32 s19, s19, 0
	global_load_dword v173, v246, s[18:19] offset:0
	global_load_dword v174, v246, s[18:19] offset:64
	global_load_dword v175, v246, s[18:19] offset:128
	global_load_dword v176, v246, s[18:19] offset:192
	s_add_u32 s18, s18, 0x1000
	s_addc_u32 s19, s19, 0
	global_load_dword v177, v246, s[18:19] offset:0
	global_load_dword v178, v246, s[18:19] offset:64
	global_load_dword v179, v246, s[18:19] offset:128
	global_load_dword v180, v246, s[18:19] offset:192
	s_add_u32 s18, s18, 0x1000
	s_addc_u32 s19, s19, 0
	global_load_dword v181, v246, s[18:19] offset:0
	global_load_dword v182, v246, s[18:19] offset:64
	global_load_dword v183, v246, s[18:19] offset:128
	global_load_dword v184, v246, s[18:19] offset:192
	s_add_u32 s18, s18, 0xd000
	s_addc_u32 s19, s19, 0
	global_load_dword v185, v246, s[18:19] offset:0
	global_load_dword v186, v246, s[18:19] offset:64
	global_load_dword v187, v246, s[18:19] offset:128
	global_load_dword v188, v246, s[18:19] offset:192
	s_add_u32 s18, s18, 0x1000
	s_addc_u32 s19, s19, 0
	global_load_dword v189, v246, s[18:19] offset:0
	global_load_dword v190, v246, s[18:19] offset:64
	global_load_dword v191, v246, s[18:19] offset:128
	global_load_dword v192, v246, s[18:19] offset:192
	s_add_u32 s18, s18, 0x1000
	s_addc_u32 s19, s19, 0
	global_load_dword v193, v246, s[18:19] offset:0
	global_load_dword v194, v246, s[18:19] offset:64
	global_load_dword v195, v246, s[18:19] offset:128
	global_load_dword v196, v246, s[18:19] offset:192
	s_add_u32 s18, s18, 0x1000
	s_addc_u32 s19, s19, 0
	global_load_dword v197, v246, s[18:19] offset:0
	global_load_dword v198, v246, s[18:19] offset:64
	global_load_dword v199, v246, s[18:19] offset:128
	global_load_dword v200, v246, s[18:19] offset:192
	s_waitcnt vmcnt(63)
	s_barrier
	ds_read_b128 v[64:67], v252 offset:0
	ds_read_b128 v[96:99], v254 offset:32768
	ds_read_b128 v[100:103], v254 offset:34816
	ds_read_b128 v[104:107], v254 offset:36864
	ds_read_b128 v[108:111], v254 offset:38912
	ds_read_b128 v[68:71], v252 offset:2048
	ds_read_b128 v[72:75], v252 offset:4096
	ds_read_b128 v[76:79], v252 offset:6144
	ds_read_b128 v[80:83], v253 offset:0
	ds_read_b128 v[112:115], v255 offset:32768
	ds_read_b128 v[116:119], v255 offset:34816
	ds_read_b128 v[120:123], v255 offset:36864
	ds_read_b128 v[124:127], v255 offset:38912
	s_waitcnt lgkmcnt(11)
	v_mfma_f32_16x16x32_bf16 v[0:3], v[64:67], v[96:99], v[0:3]
	s_waitcnt lgkmcnt(10)
	v_mfma_f32_16x16x32_bf16 v[4:7], v[64:67], v[100:103], v[4:7]
	s_waitcnt lgkmcnt(9)
	v_mfma_f32_16x16x32_bf16 v[8:11], v[64:67], v[104:107], v[8:11]
	s_waitcnt lgkmcnt(8)
	v_mfma_f32_16x16x32_bf16 v[12:15], v[64:67], v[108:111], v[12:15]
	ds_read_b128 v[84:87], v253 offset:2048
	ds_read_b128 v[88:91], v253 offset:4096
	ds_read_b128 v[92:95], v253 offset:6144
	s_waitcnt lgkmcnt(10)
	v_mfma_f32_16x16x32_bf16 v[16:19], v[68:71], v[96:99], v[16:19]
	v_mfma_f32_16x16x32_bf16 v[20:23], v[68:71], v[100:103], v[20:23]
	v_mfma_f32_16x16x32_bf16 v[24:27], v[68:71], v[104:107], v[24:27]
	v_mfma_f32_16x16x32_bf16 v[28:31], v[68:71], v[108:111], v[28:31]
	s_waitcnt lgkmcnt(0)
	s_barrier
	s_add_u32 m0, s12, 0x0
	v_mfma_f32_16x16x32_bf16 v[32:35], v[72:75], v[96:99], v[32:35]
	global_load_lds_dwordx4 v248, s[8:9]
	s_add_u32 m0, s12, 0x400
	v_mfma_f32_16x16x32_bf16 v[36:39], v[72:75], v[100:103], v[36:39]
	global_load_lds_dwordx4 v249, s[8:9]
	s_add_u32 m0, s12, 0x800
	v_mfma_f32_16x16x32_bf16 v[40:43], v[72:75], v[104:107], v[40:43]
	global_load_lds_dwordx4 v250, s[8:9]
	s_add_u32 m0, s12, 0xc00
	v_mfma_f32_16x16x32_bf16 v[44:47], v[72:75], v[108:111], v[44:47]
	global_load_lds_dwordx4 v251, s[8:9]
	s_add_u32 m0, s12, 0x8000
	v_mfma_f32_16x16x32_bf16 v[48:51], v[76:79], v[96:99], v[48:51]
	global_load_lds_dwordx4 v248, s[10:11]
	s_add_u32 m0, s12, 0x8400
	v_mfma_f32_16x16x32_bf16 v[52:55], v[76:79], v[100:103], v[52:55]
	global_load_lds_dwordx4 v249, s[10:11]
	s_add_u32 m0, s12, 0x8800
	v_mfma_f32_16x16x32_bf16 v[56:59], v[76:79], v[104:107], v[56:59]
	global_load_lds_dwordx4 v250, s[10:11]
	s_add_u32 m0, s12, 0x8c00
	v_mfma_f32_16x16x32_bf16 v[60:63], v[76:79], v[108:111], v[60:63]
	global_load_lds_dwordx4 v251, s[10:11]
	s_add_u32 s8, s8, 0x80
	s_addc_u32 s9, s9, 0
	s_add_u32 s10, s10, 0x80
	s_addc_u32 s11, s11, 0
	s_waitcnt vmcnt(63)
	s_barrier
	ds_read_b128 v[64:67], v252 offset:16384
	ds_read_b128 v[96:99], v254 offset:49152
	ds_read_b128 v[100:103], v254 offset:51200
	ds_read_b128 v[104:107], v254 offset:53248
	ds_read_b128 v[108:111], v254 offset:55296
	ds_read_b128 v[68:71], v252 offset:18432
	ds_read_b128 v[72:75], v252 offset:20480
	ds_read_b128 v[76:79], v252 offset:22528
	v_mfma_f32_16x16x32_bf16 v[0:3], v[80:83], v[112:115], v[0:3]
	v_mfma_f32_16x16x32_bf16 v[4:7], v[80:83], v[116:119], v[4:7]
	v_mfma_f32_16x16x32_bf16 v[8:11], v[80:83], v[120:123], v[8:11]
	v_mfma_f32_16x16x32_bf16 v[12:15], v[80:83], v[124:127], v[12:15]
	v_mfma_f32_16x16x32_bf16 v[16:19], v[84:87], v[112:115], v[16:19]
	v_mfma_f32_16x16x32_bf16 v[20:23], v[84:87], v[116:119], v[20:23]
	v_mfma_f32_16x16x32_bf16 v[24:27], v[84:87], v[120:123], v[24:27]
	v_mfma_f32_16x16x32_bf16 v[28:31], v[84:87], v[124:127], v[28:31]
	v_mfma_f32_16x16x32_bf16 v[32:35], v[88:91], v[112:115], v[32:35]
	v_mfma_f32_16x16x32_bf16 v[36:39], v[88:91], v[116:119], v[36:39]
	v_mfma_f32_16x16x32_bf16 v[40:43], v[88:91], v[120:123], v[40:43]
	v_mfma_f32_16x16x32_bf16 v[44:47], v[88:91], v[124:127], v[44:47]
	v_mfma_f32_16x16x32_bf16 v[48:51], v[92:95], v[112:115], v[48:51]
	v_mfma_f32_16x16x32_bf16 v[52:55], v[92:95], v[116:119], v[52:55]
	v_mfma_f32_16x16x32_bf16 v[56:59], v[92:95], v[120:123], v[56:59]
	v_mfma_f32_16x16x32_bf16 v[60:63], v[92:95], v[124:127], v[60:63]
	ds_read_b128 v[80:83], v253 offset:16384
	ds_read_b128 v[112:115], v255 offset:49152
	ds_read_b128 v[116:119], v255 offset:51200
	ds_read_b128 v[120:123], v255 offset:53248
	ds_read_b128 v[124:127], v255 offset:55296
	ds_read_b128 v[84:87], v253 offset:18432
	ds_read_b128 v[88:91], v253 offset:20480
	ds_read_b128 v[92:95], v253 offset:22528
	s_waitcnt lgkmcnt(14)
	v_mfma_f32_16x16x32_bf16 v[0:3], v[64:67], v[96:99], v[0:3]
	s_waitcnt lgkmcnt(13)
	v_mfma_f32_16x16x32_bf16 v[4:7], v[64:67], v[100:103], v[4:7]
	s_waitcnt lgkmcnt(12)
	v_mfma_f32_16x16x32_bf16 v[8:11], v[64:67], v[104:107], v[8:11]
	s_waitcnt lgkmcnt(11)
	v_mfma_f32_16x16x32_bf16 v[12:15], v[64:67], v[108:111], v[12:15]
	s_waitcnt lgkmcnt(10)
	v_mfma_f32_16x16x32_bf16 v[16:19], v[68:71], v[96:99], v[16:19]
	v_mfma_f32_16x16x32_bf16 v[20:23], v[68:71], v[100:103], v[20:23]
	v_mfma_f32_16x16x32_bf16 v[24:27], v[68:71], v[104:107], v[24:27]
	v_mfma_f32_16x16x32_bf16 v[28:31], v[68:71], v[108:111], v[28:31]
	s_waitcnt lgkmcnt(0)
	s_barrier
	s_add_u32 m0, s12, 0x4000
	v_mfma_f32_16x16x32_bf16 v[32:35], v[72:75], v[96:99], v[32:35]
	global_load_lds_dwordx4 v248, s[8:9]
	s_add_u32 m0, s12, 0x4400
	v_mfma_f32_16x16x32_bf16 v[36:39], v[72:75], v[100:103], v[36:39]
	global_load_lds_dwordx4 v249, s[8:9]
	s_add_u32 m0, s12, 0x4800
	v_mfma_f32_16x16x32_bf16 v[40:43], v[72:75], v[104:107], v[40:43]
	global_load_lds_dwordx4 v250, s[8:9]
	s_add_u32 m0, s12, 0x4c00
	v_mfma_f32_16x16x32_bf16 v[44:47], v[72:75], v[108:111], v[44:47]
	global_load_lds_dwordx4 v251, s[8:9]
	s_add_u32 m0, s12, 0xc000
	v_mfma_f32_16x16x32_bf16 v[48:51], v[76:79], v[96:99], v[48:51]
	global_load_lds_dwordx4 v248, s[10:11]
	s_add_u32 m0, s12, 0xc400
	v_mfma_f32_16x16x32_bf16 v[52:55], v[76:79], v[100:103], v[52:55]
	global_load_lds_dwordx4 v249, s[10:11]
	s_add_u32 m0, s12, 0xc800
	v_mfma_f32_16x16x32_bf16 v[56:59], v[76:79], v[104:107], v[56:59]
	global_load_lds_dwordx4 v250, s[10:11]
	s_add_u32 m0, s12, 0xcc00
	v_mfma_f32_16x16x32_bf16 v[60:63], v[76:79], v[108:111], v[60:63]
	global_load_lds_dwordx4 v251, s[10:11]
	s_add_u32 s8, s8, 0x80
	s_addc_u32 s9, s9, 0
	s_add_u32 s10, s10, 0x80
	s_addc_u32 s11, s11, 0
	s_mov_b32 s13, 20

.Lr13_tile:
	s_cmp_lt_u32 s15, 0x200
	s_cbranch_scc0 .Lr13_end
	s_and_b32 s2, s15, 63
	s_lshr_b32 s3, s15, 6
	s_mul_i32 s14, s2, 0x40000
	s_add_u32 s8, s26, s14
	s_addc_u32 s9, s27, 0
	s_mul_i32 s14, s3, 0x40000
	s_add_u32 s10, s28, s14
	s_addc_u32 s11, s29, 0
	s_lshl_b32 s14, s2, 19
	s_lshl_b32 s6, s3, 9
	s_add_u32 s14, s14, s6
	s_add_u32 s20, s4, 0x6b7a100
	s_addc_u32 s21, s5, 0
	s_add_u32 s20, s20, s14
	s_addc_u32 s21, s21, 0
	s_sub_u32 s7, s2, 32
	s_lshr_b32 s7, s7, 3
	s_add_u32 s7, s7, 1
	s_cmp_lt_u32 s2, 32
	s_cselect_b32 s7, 0, s7
	s_mul_i32 s7, s7, 0x6000
	s_add_u32 s7, s7, s6
	s_add_u32 s22, s4, 0x6b22000
	s_addc_u32 s23, s5, 0
	s_add_u32 s22, s22, s7
	s_addc_u32 s23, s23, 0
	s_add_u32 s30, s24, 0x0
	s_addc_u32 s31, s25, 0
	s_add_u32 s30, s30, s6
	s_addc_u32 s31, s31, 0
	v_readfirstlane_b32 s12, v247
	s_lshl_b32 s12, s12, 12
	s_add_u32 m0, s12, 0x0
	v_mov_b32_e32 v0, 0
	global_load_lds_dwordx4 v248, s[8:9]
	v_mov_b32_e32 v1, 0
	s_add_u32 m0, s12, 0x400
	v_mov_b32_e32 v2, 0
	global_load_lds_dwordx4 v249, s[8:9]
	v_mov_b32_e32 v3, 0
	s_add_u32 m0, s12, 0x800
	v_mov_b32_e32 v4, 0
	global_load_lds_dwordx4 v250, s[8:9]
	v_mov_b32_e32 v5, 0
	s_add_u32 m0, s12, 0xc00
	v_mov_b32_e32 v6, 0
	global_load_lds_dwordx4 v251, s[8:9]
	v_mov_b32_e32 v7, 0
	s_add_u32 m0, s12, 0x8000
	v_mov_b32_e32 v8, 0
	global_load_lds_dwordx4 v248, s[10:11]
	v_mov_b32_e32 v9, 0
	s_add_u32 m0, s12, 0x8400
	v_mov_b32_e32 v10, 0
	global_load_lds_dwordx4 v249, s[10:11]
	v_mov_b32_e32 v11, 0
	s_add_u32 m0, s12, 0x8800
	v_mov_b32_e32 v12, 0
	global_load_lds_dwordx4 v250, s[10:11]
	v_mov_b32_e32 v13, 0
	s_add_u32 m0, s12, 0x8c00
	v_mov_b32_e32 v14, 0
	global_load_lds_dwordx4 v251, s[10:11]
	v_mov_b32_e32 v15, 0
	s_add_u32 s8, s8, 0x80
	s_addc_u32 s9, s9, 0
	s_add_u32 s10, s10, 0x80
	s_addc_u32 s11, s11, 0
	s_add_u32 m0, s12, 0x4000
	v_mov_b32_e32 v16, 0
	global_load_lds_dwordx4 v248, s[8:9]
	v_mov_b32_e32 v17, 0
	s_add_u32 m0, s12, 0x4400
	v_mov_b32_e32 v18, 0
	global_load_lds_dwordx4 v249, s[8:9]
	v_mov_b32_e32 v19, 0
	s_add_u32 m0, s12, 0x4800
	v_mov_b32_e32 v20, 0
	global_load_lds_dwordx4 v250, s[8:9]
	v_mov_b32_e32 v21, 0
	s_add_u32 m0, s12, 0x4c00
	v_mov_b32_e32 v22, 0
	global_load_lds_dwordx4 v251, s[8:9]
	v_mov_b32_e32 v23, 0
	s_add_u32 m0, s12, 0xc000
	v_mov_b32_e32 v24, 0
	global_load_lds_dwordx4 v248, s[10:11]
	v_mov_b32_e32 v25, 0
	s_add_u32 m0, s12, 0xc400
	v_mov_b32_e32 v26, 0
	global_load_lds_dwordx4 v249, s[10:11]
	v_mov_b32_e32 v27, 0
	s_add_u32 m0, s12, 0xc800
	v_mov_b32_e32 v28, 0
	global_load_lds_dwordx4 v250, s[10:11]
	v_mov_b32_e32 v29, 0
	s_add_u32 m0, s12, 0xcc00
	v_mov_b32_e32 v30, 0
	global_load_lds_dwordx4 v251, s[10:11]
	v_mov_b32_e32 v31, 0
	s_add_u32 s8, s8, 0x80
	s_addc_u32 s9, s9, 0
	s_add_u32 s10, s10, 0x80
	s_addc_u32 s11, s11, 0
	v_mov_b32_e32 v32, 0
	v_mov_b32_e32 v33, 0
	v_mov_b32_e32 v34, 0
	v_mov_b32_e32 v35, 0
	v_mov_b32_e32 v36, 0
	v_mov_b32_e32 v37, 0
	v_mov_b32_e32 v38, 0
	v_mov_b32_e32 v39, 0
	v_mov_b32_e32 v40, 0
	v_mov_b32_e32 v41, 0
	v_mov_b32_e32 v42, 0
	v_mov_b32_e32 v43, 0
	v_mov_b32_e32 v44, 0
	v_mov_b32_e32 v45, 0
	v_mov_b32_e32 v46, 0
	v_mov_b32_e32 v47, 0
	v_mov_b32_e32 v48, 0
	v_mov_b32_e32 v49, 0
	v_mov_b32_e32 v50, 0
	v_mov_b32_e32 v51, 0
	v_mov_b32_e32 v52, 0
	v_mov_b32_e32 v53, 0
	v_mov_b32_e32 v54, 0
	v_mov_b32_e32 v55, 0
	v_mov_b32_e32 v56, 0
	v_mov_b32_e32 v57, 0
	v_mov_b32_e32 v58, 0
	v_mov_b32_e32 v59, 0
	v_mov_b32_e32 v60, 0
	v_mov_b32_e32 v61, 0
	v_mov_b32_e32 v62, 0
	v_mov_b32_e32 v63, 0
	global_load_dword v201, v245, s[22:23] offset:0
	global_load_dword v202, v245, s[22:23] offset:64
	global_load_dword v203, v245, s[22:23] offset:128
	global_load_dword v204, v245, s[22:23] offset:192
	global_load_dword v205, v245, s[30:31] offset:0
	global_load_dword v206, v245, s[30:31] offset:64
	global_load_dword v207, v245, s[30:31] offset:128
	global_load_dword v208, v245, s[30:31] offset:192
	s_mov_b64 s[18:19], s[20:21]
	global_load_dword v129, v246, s[18:19] offset:0
	global_load_dword v130, v246, s[18:19] offset:64
	global_load_dword v131, v246, s[18:19] offset:128
	global_load_dword v132, v246, s[18:19] offset:192
	s_add_u32 s18, s18, 0x1000
	s_addc_u32 s19, s19, 0
	global_load_dword v133, v246, s[18:19] offset:0
	global_load_dword v134, v246, s[18:19] offset:64
	global_load_dword v135, v246, s[18:19] offset:128
	global_load_dword v136, v246, s[18:19] offset:192
	s_add_u32 s18, s18, 0x1000
	s_addc_u32 s19, s19, 0
	global_load_dword v137, v246, s[18:19] offset:0
	global_load_dword v138, v246, s[18:19] offset:64
	global_load_dword v139, v246, s[18:19] offset:128
	global_load_dword v140, v246, s[18:19] offset:192
	s_add_u32 s18, s18, 0x1000
	s_addc_u32 s19, s19, 0
	global_load_dword v141, v246, s[18:19] offset:0
	global_load_dword v142, v246, s[18:19] offset:64
	global_load_dword v143, v246, s[18:19] offset:128
	global_load_dword v144, v246, s[18:19] offset:192
	s_add_u32 s18, s18, 0xd000
	s_addc_u32 s19, s19, 0
	global_load_dword v145, v246, s[18:19] offset:0
	global_load_dword v146, v246, s[18:19] offset:64
	global_load_dword v147, v246, s[18:19] offset:128
	global_load_dword v148, v246, s[18:19] offset:192
	s_add_u32 s18, s18, 0x1000
	s_addc_u32 s19, s19, 0
	global_load_dword v149, v246, s[18:19] offset:0
	global_load_dword v150, v246, s[18:19] offset:64
	global_load_dword v151, v246, s[18:19] offset:128
	global_load_dword v152, v246, s[18:19] offset:192
	s_add_u32 s18, s18, 0x1000
	s_addc_u32 s19, s19, 0
	global_load_dword v153, v246, s[18:19] offset:0
	global_load_dword v154, v246, s[18:19] offset:64
	global_load_dword v155, v246, s[18:19] offset:128
	global_load_dword v156, v246, s[18:19] offset:192
	s_add_u32 s18, s18, 0x1000
	s_addc_u32 s19, s19, 0
	global_load_dword v157, v246, s[18:19] offset:0
	global_load_dword v158, v246, s[18:19] offset:64
	global_load_dword v159, v246, s[18:19] offset:128
	global_load_dword v160, v246, s[18:19] offset:192
	s_add_u32 s18, s18, 0xd000
	s_addc_u32 s19, s19, 0
	global_load_dword v161, v246, s[18:19] offset:0
	global_load_dword v170, v246, s[18:19] offset:64
	global_load_dword v171, v246, s[18:19] offset:128
	global_load_dword v172, v246, s[18:19] offset:192
	s_add_u32 s18, s18, 0x1000
	s_addc_u32 s19, s19, 0
	global_load_dword v173, v246, s[18:19] offset:0
	global_load_dword v174, v246, s[18:19] offset:64
	global_load_dword v175, v246, s[18:19] offset:128
	global_load_dword v176, v246, s[18:19] offset:192
	s_add_u32 s18, s18, 0x1000
	s_addc_u32 s19, s19, 0
	global_load_dword v177, v246, s[18:19] offset:0
	global_load_dword v178, v246, s[18:19] offset:64
	global_load_dword v179, v246, s[18:19] offset:128
	global_load_dword v180, v246, s[18:19] offset:192
	s_add_u32 s18, s18, 0x1000
	s_addc_u32 s19, s19, 0
	global_load_dword v181, v246, s[18:19] offset:0
	global_load_dword v182, v246, s[18:19] offset:64
	global_load_dword v183, v246, s[18:19] offset:128
	global_load_dword v184, v246, s[18:19] offset:192
	s_add_u32 s18, s18, 0xd000
	s_addc_u32 s19, s19, 0
	global_load_dword v185, v246, s[18:19] offset:0
	global_load_dword v186, v246, s[18:19] offset:64
	global_load_dword v187, v246, s[18:19] offset:128
	global_load_dword v188, v246, s[18:19] offset:192
	s_add_u32 s18, s18, 0x1000
	s_addc_u32 s19, s19, 0
	global_load_dword v189, v246, s[18:19] offset:0
	global_load_dword v190, v246, s[18:19] offset:64
	global_load_dword v191, v246, s[18:19] offset:128
	global_load_dword v192, v246, s[18:19] offset:192
	s_add_u32 s18, s18, 0x1000
	s_addc_u32 s19, s19, 0
	global_load_dword v193, v246, s[18:19] offset:0
	global_load_dword v194, v246, s[18:19] offset:64
	global_load_dword v195, v246, s[18:19] offset:128
	global_load_dword v196, v246, s[18:19] offset:192
	s_add_u32 s18, s18, 0x1000
	s_addc_u32 s19, s19, 0
	global_load_dword v197, v246, s[18:19] offset:0
	global_load_dword v198, v246, s[18:19] offset:64
	global_load_dword v199, v246, s[18:19] offset:128
	global_load_dword v200, v246, s[18:19] offset:192
	s_waitcnt vmcnt(63)
	s_barrier
	ds_read_b128 v[64:67], v252 offset:0
	ds_read_b128 v[96:99], v254 offset:32768
	ds_read_b128 v[100:103], v254 offset:34816
	ds_read_b128 v[104:107], v254 offset:36864
	ds_read_b128 v[108:111], v254 offset:38912
	ds_read_b128 v[68:71], v252 offset:2048
	ds_read_b128 v[72:75], v252 offset:4096
	ds_read_b128 v[76:79], v252 offset:6144
	ds_read_b128 v[80:83], v253 offset:0
	ds_read_b128 v[112:115], v255 offset:32768
	ds_read_b128 v[116:119], v255 offset:34816
	ds_read_b128 v[120:123], v255 offset:36864
	ds_read_b128 v[124:127], v255 offset:38912
	s_waitcnt lgkmcnt(11)
	v_mfma_f32_16x16x32_bf16 v[0:3], v[64:67], v[96:99], v[0:3]
	s_waitcnt lgkmcnt(10)
	v_mfma_f32_16x16x32_bf16 v[4:7], v[64:67], v[100:103], v[4:7]
	s_waitcnt lgkmcnt(9)
	v_mfma_f32_16x16x32_bf16 v[8:11], v[64:67], v[104:107], v[8:11]
	s_waitcnt lgkmcnt(8)
	v_mfma_f32_16x16x32_bf16 v[12:15], v[64:67], v[108:111], v[12:15]
	ds_read_b128 v[84:87], v253 offset:2048
	ds_read_b128 v[88:91], v253 offset:4096
	ds_read_b128 v[92:95], v253 offset:6144
	s_waitcnt lgkmcnt(10)
	v_mfma_f32_16x16x32_bf16 v[16:19], v[68:71], v[96:99], v[16:19]
	v_mfma_f32_16x16x32_bf16 v[20:23], v[68:71], v[100:103], v[20:23]
	v_mfma_f32_16x16x32_bf16 v[24:27], v[68:71], v[104:107], v[24:27]
	v_mfma_f32_16x16x32_bf16 v[28:31], v[68:71], v[108:111], v[28:31]
	s_waitcnt lgkmcnt(0)
	s_barrier
	s_add_u32 m0, s12, 0x0
	v_mfma_f32_16x16x32_bf16 v[32:35], v[72:75], v[96:99], v[32:35]
	global_load_lds_dwordx4 v248, s[8:9]
	s_add_u32 m0, s12, 0x400
	v_mfma_f32_16x16x32_bf16 v[36:39], v[72:75], v[100:103], v[36:39]
	global_load_lds_dwordx4 v249, s[8:9]
	s_add_u32 m0, s12, 0x800
	v_mfma_f32_16x16x32_bf16 v[40:43], v[72:75], v[104:107], v[40:43]
	global_load_lds_dwordx4 v250, s[8:9]
	s_add_u32 m0, s12, 0xc00
	v_mfma_f32_16x16x32_bf16 v[44:47], v[72:75], v[108:111], v[44:47]
	global_load_lds_dwordx4 v251, s[8:9]
	s_add_u32 m0, s12, 0x8000
	v_mfma_f32_16x16x32_bf16 v[48:51], v[76:79], v[96:99], v[48:51]
	global_load_lds_dwordx4 v248, s[10:11]
	s_add_u32 m0, s12, 0x8400
	v_mfma_f32_16x16x32_bf16 v[52:55], v[76:79], v[100:103], v[52:55]
	global_load_lds_dwordx4 v249, s[10:11]
	s_add_u32 m0, s12, 0x8800
	v_mfma_f32_16x16x32_bf16 v[56:59], v[76:79], v[104:107], v[56:59]
	global_load_lds_dwordx4 v250, s[10:11]
	s_add_u32 m0, s12, 0x8c00
	v_mfma_f32_16x16x32_bf16 v[60:63], v[76:79], v[108:111], v[60:63]
	global_load_lds_dwordx4 v251, s[10:11]
	s_add_u32 s8, s8, 0x80
	s_addc_u32 s9, s9, 0
	s_add_u32 s10, s10, 0x80
	s_addc_u32 s11, s11, 0
	s_waitcnt vmcnt(63)
	s_barrier
	ds_read_b128 v[64:67], v252 offset:16384
	ds_read_b128 v[96:99], v254 offset:49152
	ds_read_b128 v[100:103], v254 offset:51200
	ds_read_b128 v[104:107], v254 offset:53248
	ds_read_b128 v[108:111], v254 offset:55296
	ds_read_b128 v[68:71], v252 offset:18432
	ds_read_b128 v[72:75], v252 offset:20480
	ds_read_b128 v[76:79], v252 offset:22528
	v_mfma_f32_16x16x32_bf16 v[0:3], v[80:83], v[112:115], v[0:3]
	v_mfma_f32_16x16x32_bf16 v[4:7], v[80:83], v[116:119], v[4:7]
	v_mfma_f32_16x16x32_bf16 v[8:11], v[80:83], v[120:123], v[8:11]
	v_mfma_f32_16x16x32_bf16 v[12:15], v[80:83], v[124:127], v[12:15]
	v_mfma_f32_16x16x32_bf16 v[16:19], v[84:87], v[112:115], v[16:19]
	v_mfma_f32_16x16x32_bf16 v[20:23], v[84:87], v[116:119], v[20:23]
	v_mfma_f32_16x16x32_bf16 v[24:27], v[84:87], v[120:123], v[24:27]
	v_mfma_f32_16x16x32_bf16 v[28:31], v[84:87], v[124:127], v[28:31]
	v_mfma_f32_16x16x32_bf16 v[32:35], v[88:91], v[112:115], v[32:35]
	v_mfma_f32_16x16x32_bf16 v[36:39], v[88:91], v[116:119], v[36:39]
	v_mfma_f32_16x16x32_bf16 v[40:43], v[88:91], v[120:123], v[40:43]
	v_mfma_f32_16x16x32_bf16 v[44:47], v[88:91], v[124:127], v[44:47]
	v_mfma_f32_16x16x32_bf16 v[48:51], v[92:95], v[112:115], v[48:51]
	v_mfma_f32_16x16x32_bf16 v[52:55], v[92:95], v[116:119], v[52:55]
	v_mfma_f32_16x16x32_bf16 v[56:59], v[92:95], v[120:123], v[56:59]
	v_mfma_f32_16x16x32_bf16 v[60:63], v[92:95], v[124:127], v[60:63]
	ds_read_b128 v[80:83], v253 offset:16384
	ds_read_b128 v[112:115], v255 offset:49152
	ds_read_b128 v[116:119], v255 offset:51200
	ds_read_b128 v[120:123], v255 offset:53248
	ds_read_b128 v[124:127], v255 offset:55296
	ds_read_b128 v[84:87], v253 offset:18432
	ds_read_b128 v[88:91], v253 offset:20480
	ds_read_b128 v[92:95], v253 offset:22528
	s_waitcnt lgkmcnt(14)
	v_mfma_f32_16x16x32_bf16 v[0:3], v[64:67], v[96:99], v[0:3]
	s_waitcnt lgkmcnt(13)
	v_mfma_f32_16x16x32_bf16 v[4:7], v[64:67], v[100:103], v[4:7]
	s_waitcnt lgkmcnt(12)
	v_mfma_f32_16x16x32_bf16 v[8:11], v[64:67], v[104:107], v[8:11]
	s_waitcnt lgkmcnt(11)
	v_mfma_f32_16x16x32_bf16 v[12:15], v[64:67], v[108:111], v[12:15]
	s_waitcnt lgkmcnt(10)
	v_mfma_f32_16x16x32_bf16 v[16:19], v[68:71], v[96:99], v[16:19]
	v_mfma_f32_16x16x32_bf16 v[20:23], v[68:71], v[100:103], v[20:23]
	v_mfma_f32_16x16x32_bf16 v[24:27], v[68:71], v[104:107], v[24:27]
	v_mfma_f32_16x16x32_bf16 v[28:31], v[68:71], v[108:111], v[28:31]
	s_waitcnt lgkmcnt(0)
	s_barrier
	s_add_u32 m0, s12, 0x4000
	v_mfma_f32_16x16x32_bf16 v[32:35], v[72:75], v[96:99], v[32:35]
	global_load_lds_dwordx4 v248, s[8:9]
	s_add_u32 m0, s12, 0x4400
	v_mfma_f32_16x16x32_bf16 v[36:39], v[72:75], v[100:103], v[36:39]
	global_load_lds_dwordx4 v249, s[8:9]
	s_add_u32 m0, s12, 0x4800
	v_mfma_f32_16x16x32_bf16 v[40:43], v[72:75], v[104:107], v[40:43]
	global_load_lds_dwordx4 v250, s[8:9]
	s_add_u32 m0, s12, 0x4c00
	v_mfma_f32_16x16x32_bf16 v[44:47], v[72:75], v[108:111], v[44:47]
	global_load_lds_dwordx4 v251, s[8:9]
	s_add_u32 m0, s12, 0xc000
	v_mfma_f32_16x16x32_bf16 v[48:51], v[76:79], v[96:99], v[48:51]
	global_load_lds_dwordx4 v248, s[10:11]
	s_add_u32 m0, s12, 0xc400
	v_mfma_f32_16x16x32_bf16 v[52:55], v[76:79], v[100:103], v[52:55]
	global_load_lds_dwordx4 v249, s[10:11]
	s_add_u32 m0, s12, 0xc800
	v_mfma_f32_16x16x32_bf16 v[56:59], v[76:79], v[104:107], v[56:59]
	global_load_lds_dwordx4 v250, s[10:11]
	s_add_u32 m0, s12, 0xcc00
	v_mfma_f32_16x16x32_bf16 v[60:63], v[76:79], v[108:111], v[60:63]
	global_load_lds_dwordx4 v251, s[10:11]
	s_add_u32 s8, s8, 0x80
	s_addc_u32 s9, s9, 0
	s_add_u32 s10, s10, 0x80
	s_addc_u32 s11, s11, 0
	s_mov_b32 s13, 6

.Lr16_tile:
	s_cmp_lt_u32 s15, 0x200
	s_cbranch_scc0 .Lr16_end
	s_and_b32 s2, s15, 63
	s_lshr_b32 s3, s15, 6
	s_mul_i32 s14, s2, 0xb0000
	s_add_u32 s8, s26, s14
	s_addc_u32 s9, s27, 0
	s_mul_i32 s14, s3, 0xb0000
	s_add_u32 s10, s28, s14
	s_addc_u32 s11, s29, 0
	s_lshl_b32 s14, s2, 19
	s_lshl_b32 s6, s3, 9
	s_add_u32 s14, s14, s6
	s_add_u32 s20, s4, 0x6b7a100
	s_addc_u32 s21, s5, 0
	s_add_u32 s20, s20, s14
	s_addc_u32 s21, s21, 0
	s_sub_u32 s7, s2, 32
	s_lshr_b32 s7, s7, 3
	s_add_u32 s7, s7, 1
	s_cmp_lt_u32 s2, 32
	s_cselect_b32 s7, 0, s7
	s_mul_i32 s7, s7, 0x6000
	s_add_u32 s7, s7, s6
	s_add_u32 s22, s4, 0x6b25000
	s_addc_u32 s23, s5, 0
	s_add_u32 s22, s22, s7
	s_addc_u32 s23, s23, 0
	v_readfirstlane_b32 s12, v247
	s_lshl_b32 s12, s12, 12
	s_add_u32 m0, s12, 0x0
	v_mov_b32_e32 v0, 0
	global_load_lds_dwordx4 v248, s[8:9]
	v_mov_b32_e32 v1, 0
	s_add_u32 m0, s12, 0x400
	v_mov_b32_e32 v2, 0
	global_load_lds_dwordx4 v249, s[8:9]
	v_mov_b32_e32 v3, 0
	s_add_u32 m0, s12, 0x800
	v_mov_b32_e32 v4, 0
	global_load_lds_dwordx4 v250, s[8:9]
	v_mov_b32_e32 v5, 0
	s_add_u32 m0, s12, 0xc00
	v_mov_b32_e32 v6, 0
	global_load_lds_dwordx4 v251, s[8:9]
	v_mov_b32_e32 v7, 0
	s_add_u32 m0, s12, 0x8000
	v_mov_b32_e32 v8, 0
	global_load_lds_dwordx4 v248, s[10:11]
	v_mov_b32_e32 v9, 0
	s_add_u32 m0, s12, 0x8400
	v_mov_b32_e32 v10, 0
	global_load_lds_dwordx4 v249, s[10:11]
	v_mov_b32_e32 v11, 0
	s_add_u32 m0, s12, 0x8800
	v_mov_b32_e32 v12, 0
	global_load_lds_dwordx4 v250, s[10:11]
	v_mov_b32_e32 v13, 0
	s_add_u32 m0, s12, 0x8c00
	v_mov_b32_e32 v14, 0
	global_load_lds_dwordx4 v251, s[10:11]
	v_mov_b32_e32 v15, 0
	s_add_u32 s8, s8, 0x80
	s_addc_u32 s9, s9, 0
	s_add_u32 s10, s10, 0x80
	s_addc_u32 s11, s11, 0
	s_add_u32 m0, s12, 0x4000
	v_mov_b32_e32 v16, 0
	global_load_lds_dwordx4 v248, s[8:9]
	v_mov_b32_e32 v17, 0
	s_add_u32 m0, s12, 0x4400
	v_mov_b32_e32 v18, 0
	global_load_lds_dwordx4 v249, s[8:9]
	v_mov_b32_e32 v19, 0
	s_add_u32 m0, s12, 0x4800
	v_mov_b32_e32 v20, 0
	global_load_lds_dwordx4 v250, s[8:9]
	v_mov_b32_e32 v21, 0
	s_add_u32 m0, s12, 0x4c00
	v_mov_b32_e32 v22, 0
	global_load_lds_dwordx4 v251, s[8:9]
	v_mov_b32_e32 v23, 0
	s_add_u32 m0, s12, 0xc000
	v_mov_b32_e32 v24, 0
	global_load_lds_dwordx4 v248, s[10:11]
	v_mov_b32_e32 v25, 0
	s_add_u32 m0, s12, 0xc400
	v_mov_b32_e32 v26, 0
	global_load_lds_dwordx4 v249, s[10:11]
	v_mov_b32_e32 v27, 0
	s_add_u32 m0, s12, 0xc800
	v_mov_b32_e32 v28, 0
	global_load_lds_dwordx4 v250, s[10:11]
	v_mov_b32_e32 v29, 0
	s_add_u32 m0, s12, 0xcc00
	v_mov_b32_e32 v30, 0
	global_load_lds_dwordx4 v251, s[10:11]
	v_mov_b32_e32 v31, 0
	s_add_u32 s8, s8, 0x80
	s_addc_u32 s9, s9, 0
	s_add_u32 s10, s10, 0x80
	s_addc_u32 s11, s11, 0
	v_mov_b32_e32 v32, 0
	v_mov_b32_e32 v33, 0
	v_mov_b32_e32 v34, 0
	v_mov_b32_e32 v35, 0
	v_mov_b32_e32 v36, 0
	v_mov_b32_e32 v37, 0
	v_mov_b32_e32 v38, 0
	v_mov_b32_e32 v39, 0
	v_mov_b32_e32 v40, 0
	v_mov_b32_e32 v41, 0
	v_mov_b32_e32 v42, 0
	v_mov_b32_e32 v43, 0
	v_mov_b32_e32 v44, 0
	v_mov_b32_e32 v45, 0
	v_mov_b32_e32 v46, 0
	v_mov_b32_e32 v47, 0
	v_mov_b32_e32 v48, 0
	v_mov_b32_e32 v49, 0
	v_mov_b32_e32 v50, 0
	v_mov_b32_e32 v51, 0
	v_mov_b32_e32 v52, 0
	v_mov_b32_e32 v53, 0
	v_mov_b32_e32 v54, 0
	v_mov_b32_e32 v55, 0
	v_mov_b32_e32 v56, 0
	v_mov_b32_e32 v57, 0
	v_mov_b32_e32 v58, 0
	v_mov_b32_e32 v59, 0
	v_mov_b32_e32 v60, 0
	v_mov_b32_e32 v61, 0
	v_mov_b32_e32 v62, 0
	v_mov_b32_e32 v63, 0
	global_load_dword v201, v245, s[22:23] offset:0
	global_load_dword v202, v245, s[22:23] offset:64
	global_load_dword v203, v245, s[22:23] offset:128
	global_load_dword v204, v245, s[22:23] offset:192
	s_mov_b64 s[18:19], s[20:21]
	global_load_dword v129, v246, s[18:19] offset:0
	global_load_dword v130, v246, s[18:19] offset:64
	global_load_dword v131, v246, s[18:19] offset:128
	global_load_dword v132, v246, s[18:19] offset:192
	s_add_u32 s18, s18, 0x1000
	s_addc_u32 s19, s19, 0
	global_load_dword v133, v246, s[18:19] offset:0
	global_load_dword v134, v246, s[18:19] offset:64
	global_load_dword v135, v246, s[18:19] offset:128
	global_load_dword v136, v246, s[18:19] offset:192
	s_add_u32 s18, s18, 0x1000
	s_addc_u32 s19, s19, 0
	global_load_dword v137, v246, s[18:19] offset:0
	global_load_dword v138, v246, s[18:19] offset:64
	global_load_dword v139, v246, s[18:19] offset:128
	global_load_dword v140, v246, s[18:19] offset:192
	s_add_u32 s18, s18, 0x1000
	s_addc_u32 s19, s19, 0
	global_load_dword v141, v246, s[18:19] offset:0
	global_load_dword v142, v246, s[18:19] offset:64
	global_load_dword v143, v246, s[18:19] offset:128
	global_load_dword v144, v246, s[18:19] offset:192
	s_add_u32 s18, s18, 0xd000
	s_addc_u32 s19, s19, 0
	global_load_dword v145, v246, s[18:19] offset:0
	global_load_dword v146, v246, s[18:19] offset:64
	global_load_dword v147, v246, s[18:19] offset:128
	global_load_dword v148, v246, s[18:19] offset:192
	s_add_u32 s18, s18, 0x1000
	s_addc_u32 s19, s19, 0
	global_load_dword v149, v246, s[18:19] offset:0
	global_load_dword v150, v246, s[18:19] offset:64
	global_load_dword v151, v246, s[18:19] offset:128
	global_load_dword v152, v246, s[18:19] offset:192
	s_add_u32 s18, s18, 0x1000
	s_addc_u32 s19, s19, 0
	global_load_dword v153, v246, s[18:19] offset:0
	global_load_dword v154, v246, s[18:19] offset:64
	global_load_dword v155, v246, s[18:19] offset:128
	global_load_dword v156, v246, s[18:19] offset:192
	s_add_u32 s18, s18, 0x1000
	s_addc_u32 s19, s19, 0
	global_load_dword v157, v246, s[18:19] offset:0
	global_load_dword v158, v246, s[18:19] offset:64
	global_load_dword v159, v246, s[18:19] offset:128
	global_load_dword v160, v246, s[18:19] offset:192
	s_add_u32 s18, s18, 0xd000
	s_addc_u32 s19, s19, 0
	global_load_dword v161, v246, s[18:19] offset:0
	global_load_dword v170, v246, s[18:19] offset:64
	global_load_dword v171, v246, s[18:19] offset:128
	global_load_dword v172, v246, s[18:19] offset:192
	s_add_u32 s18, s18, 0x1000
	s_addc_u32 s19, s19, 0
	global_load_dword v173, v246, s[18:19] offset:0
	global_load_dword v174, v246, s[18:19] offset:64
	global_load_dword v175, v246, s[18:19] offset:128
	global_load_dword v176, v246, s[18:19] offset:192
	s_add_u32 s18, s18, 0x1000
	s_addc_u32 s19, s19, 0
	global_load_dword v177, v246, s[18:19] offset:0
	global_load_dword v178, v246, s[18:19] offset:64
	global_load_dword v179, v246, s[18:19] offset:128
	global_load_dword v180, v246, s[18:19] offset:192
	s_add_u32 s18, s18, 0x1000
	s_addc_u32 s19, s19, 0
	global_load_dword v181, v246, s[18:19] offset:0
	global_load_dword v182, v246, s[18:19] offset:64
	global_load_dword v183, v246, s[18:19] offset:128
	global_load_dword v184, v246, s[18:19] offset:192
	s_add_u32 s18, s18, 0xd000
	s_addc_u32 s19, s19, 0
	global_load_dword v185, v246, s[18:19] offset:0
	global_load_dword v186, v246, s[18:19] offset:64
	global_load_dword v187, v246, s[18:19] offset:128
	global_load_dword v188, v246, s[18:19] offset:192
	s_add_u32 s18, s18, 0x1000
	s_addc_u32 s19, s19, 0
	global_load_dword v189, v246, s[18:19] offset:0
	global_load_dword v190, v246, s[18:19] offset:64
	global_load_dword v191, v246, s[18:19] offset:128
	global_load_dword v192, v246, s[18:19] offset:192
	s_add_u32 s18, s18, 0x1000
	s_addc_u32 s19, s19, 0
	global_load_dword v193, v246, s[18:19] offset:0
	global_load_dword v194, v246, s[18:19] offset:64
	global_load_dword v195, v246, s[18:19] offset:128
	global_load_dword v196, v246, s[18:19] offset:192
	s_add_u32 s18, s18, 0x1000
	s_addc_u32 s19, s19, 0
	global_load_dword v197, v246, s[18:19] offset:0
	global_load_dword v198, v246, s[18:19] offset:64
	global_load_dword v199, v246, s[18:19] offset:128
	global_load_dword v200, v246, s[18:19] offset:192
	s_waitcnt vmcnt(63)
	s_barrier
	ds_read_b128 v[64:67], v252 offset:0
	ds_read_b128 v[96:99], v254 offset:32768
	ds_read_b128 v[100:103], v254 offset:34816
	ds_read_b128 v[104:107], v254 offset:36864
	ds_read_b128 v[108:111], v254 offset:38912
	ds_read_b128 v[68:71], v252 offset:2048
	ds_read_b128 v[72:75], v252 offset:4096
	ds_read_b128 v[76:79], v252 offset:6144
	ds_read_b128 v[80:83], v253 offset:0
	ds_read_b128 v[112:115], v255 offset:32768
	ds_read_b128 v[116:119], v255 offset:34816
	ds_read_b128 v[120:123], v255 offset:36864
	ds_read_b128 v[124:127], v255 offset:38912
	s_waitcnt lgkmcnt(11)
	v_mfma_f32_16x16x32_bf16 v[0:3], v[64:67], v[96:99], v[0:3]
	s_waitcnt lgkmcnt(10)
	v_mfma_f32_16x16x32_bf16 v[4:7], v[64:67], v[100:103], v[4:7]
	s_waitcnt lgkmcnt(9)
	v_mfma_f32_16x16x32_bf16 v[8:11], v[64:67], v[104:107], v[8:11]
	s_waitcnt lgkmcnt(8)
	v_mfma_f32_16x16x32_bf16 v[12:15], v[64:67], v[108:111], v[12:15]
	ds_read_b128 v[84:87], v253 offset:2048
	ds_read_b128 v[88:91], v253 offset:4096
	ds_read_b128 v[92:95], v253 offset:6144
	s_waitcnt lgkmcnt(10)
	v_mfma_f32_16x16x32_bf16 v[16:19], v[68:71], v[96:99], v[16:19]
	v_mfma_f32_16x16x32_bf16 v[20:23], v[68:71], v[100:103], v[20:23]
	v_mfma_f32_16x16x32_bf16 v[24:27], v[68:71], v[104:107], v[24:27]
	v_mfma_f32_16x16x32_bf16 v[28:31], v[68:71], v[108:111], v[28:31]
	s_waitcnt lgkmcnt(0)
	s_barrier
	s_add_u32 m0, s12, 0x0
	v_mfma_f32_16x16x32_bf16 v[32:35], v[72:75], v[96:99], v[32:35]
	global_load_lds_dwordx4 v248, s[8:9]
	s_add_u32 m0, s12, 0x400
	v_mfma_f32_16x16x32_bf16 v[36:39], v[72:75], v[100:103], v[36:39]
	global_load_lds_dwordx4 v249, s[8:9]
	s_add_u32 m0, s12, 0x800
	v_mfma_f32_16x16x32_bf16 v[40:43], v[72:75], v[104:107], v[40:43]
	global_load_lds_dwordx4 v250, s[8:9]
	s_add_u32 m0, s12, 0xc00
	v_mfma_f32_16x16x32_bf16 v[44:47], v[72:75], v[108:111], v[44:47]
	global_load_lds_dwordx4 v251, s[8:9]
	s_add_u32 m0, s12, 0x8000
	v_mfma_f32_16x16x32_bf16 v[48:51], v[76:79], v[96:99], v[48:51]
	global_load_lds_dwordx4 v248, s[10:11]
	s_add_u32 m0, s12, 0x8400
	v_mfma_f32_16x16x32_bf16 v[52:55], v[76:79], v[100:103], v[52:55]
	global_load_lds_dwordx4 v249, s[10:11]
	s_add_u32 m0, s12, 0x8800
	v_mfma_f32_16x16x32_bf16 v[56:59], v[76:79], v[104:107], v[56:59]
	global_load_lds_dwordx4 v250, s[10:11]
	s_add_u32 m0, s12, 0x8c00
	v_mfma_f32_16x16x32_bf16 v[60:63], v[76:79], v[108:111], v[60:63]
	global_load_lds_dwordx4 v251, s[10:11]
	s_add_u32 s8, s8, 0x80
	s_addc_u32 s9, s9, 0
	s_add_u32 s10, s10, 0x80
	s_addc_u32 s11, s11, 0
	s_waitcnt vmcnt(63)
	s_barrier
	ds_read_b128 v[64:67], v252 offset:16384
	ds_read_b128 v[96:99], v254 offset:49152
	ds_read_b128 v[100:103], v254 offset:51200
	ds_read_b128 v[104:107], v254 offset:53248
	ds_read_b128 v[108:111], v254 offset:55296
	ds_read_b128 v[68:71], v252 offset:18432
	ds_read_b128 v[72:75], v252 offset:20480
	ds_read_b128 v[76:79], v252 offset:22528
	v_mfma_f32_16x16x32_bf16 v[0:3], v[80:83], v[112:115], v[0:3]
	v_mfma_f32_16x16x32_bf16 v[4:7], v[80:83], v[116:119], v[4:7]
	v_mfma_f32_16x16x32_bf16 v[8:11], v[80:83], v[120:123], v[8:11]
	v_mfma_f32_16x16x32_bf16 v[12:15], v[80:83], v[124:127], v[12:15]
	v_mfma_f32_16x16x32_bf16 v[16:19], v[84:87], v[112:115], v[16:19]
	v_mfma_f32_16x16x32_bf16 v[20:23], v[84:87], v[116:119], v[20:23]
	v_mfma_f32_16x16x32_bf16 v[24:27], v[84:87], v[120:123], v[24:27]
	v_mfma_f32_16x16x32_bf16 v[28:31], v[84:87], v[124:127], v[28:31]
	v_mfma_f32_16x16x32_bf16 v[32:35], v[88:91], v[112:115], v[32:35]
	v_mfma_f32_16x16x32_bf16 v[36:39], v[88:91], v[116:119], v[36:39]
	v_mfma_f32_16x16x32_bf16 v[40:43], v[88:91], v[120:123], v[40:43]
	v_mfma_f32_16x16x32_bf16 v[44:47], v[88:91], v[124:127], v[44:47]
	v_mfma_f32_16x16x32_bf16 v[48:51], v[92:95], v[112:115], v[48:51]
	v_mfma_f32_16x16x32_bf16 v[52:55], v[92:95], v[116:119], v[52:55]
	v_mfma_f32_16x16x32_bf16 v[56:59], v[92:95], v[120:123], v[56:59]
	v_mfma_f32_16x16x32_bf16 v[60:63], v[92:95], v[124:127], v[60:63]
	ds_read_b128 v[80:83], v253 offset:16384
	ds_read_b128 v[112:115], v255 offset:49152
	ds_read_b128 v[116:119], v255 offset:51200
	ds_read_b128 v[120:123], v255 offset:53248
	ds_read_b128 v[124:127], v255 offset:55296
	ds_read_b128 v[84:87], v253 offset:18432
	ds_read_b128 v[88:91], v253 offset:20480
	ds_read_b128 v[92:95], v253 offset:22528
	s_waitcnt lgkmcnt(14)
	v_mfma_f32_16x16x32_bf16 v[0:3], v[64:67], v[96:99], v[0:3]
	s_waitcnt lgkmcnt(13)
	v_mfma_f32_16x16x32_bf16 v[4:7], v[64:67], v[100:103], v[4:7]
	s_waitcnt lgkmcnt(12)
	v_mfma_f32_16x16x32_bf16 v[8:11], v[64:67], v[104:107], v[8:11]
	s_waitcnt lgkmcnt(11)
	v_mfma_f32_16x16x32_bf16 v[12:15], v[64:67], v[108:111], v[12:15]
	s_waitcnt lgkmcnt(10)
	v_mfma_f32_16x16x32_bf16 v[16:19], v[68:71], v[96:99], v[16:19]
	v_mfma_f32_16x16x32_bf16 v[20:23], v[68:71], v[100:103], v[20:23]
	v_mfma_f32_16x16x32_bf16 v[24:27], v[68:71], v[104:107], v[24:27]
	v_mfma_f32_16x16x32_bf16 v[28:31], v[68:71], v[108:111], v[28:31]
	s_waitcnt lgkmcnt(0)
	s_barrier
	s_add_u32 m0, s12, 0x4000
	v_mfma_f32_16x16x32_bf16 v[32:35], v[72:75], v[96:99], v[32:35]
	global_load_lds_dwordx4 v248, s[8:9]
	s_add_u32 m0, s12, 0x4400
	v_mfma_f32_16x16x32_bf16 v[36:39], v[72:75], v[100:103], v[36:39]
	global_load_lds_dwordx4 v249, s[8:9]
	s_add_u32 m0, s12, 0x4800
	v_mfma_f32_16x16x32_bf16 v[40:43], v[72:75], v[104:107], v[40:43]
	global_load_lds_dwordx4 v250, s[8:9]
	s_add_u32 m0, s12, 0x4c00
	v_mfma_f32_16x16x32_bf16 v[44:47], v[72:75], v[108:111], v[44:47]
	global_load_lds_dwordx4 v251, s[8:9]
	s_add_u32 m0, s12, 0xc000
	v_mfma_f32_16x16x32_bf16 v[48:51], v[76:79], v[96:99], v[48:51]
	global_load_lds_dwordx4 v248, s[10:11]
	s_add_u32 m0, s12, 0xc400
	v_mfma_f32_16x16x32_bf16 v[52:55], v[76:79], v[100:103], v[52:55]
	global_load_lds_dwordx4 v249, s[10:11]
	s_add_u32 m0, s12, 0xc800
	v_mfma_f32_16x16x32_bf16 v[56:59], v[76:79], v[104:107], v[56:59]
	global_load_lds_dwordx4 v250, s[10:11]
	s_add_u32 m0, s12, 0xcc00
	v_mfma_f32_16x16x32_bf16 v[60:63], v[76:79], v[108:111], v[60:63]
	global_load_lds_dwordx4 v251, s[10:11]
	s_add_u32 s8, s8, 0x80
	s_addc_u32 s9, s9, 0
	s_add_u32 s10, s10, 0x80
	s_addc_u32 s11, s11, 0
	s_mov_b32 s13, 20

.Lr22_tile:
	s_cmp_lt_u32 s15, 0x200
	s_cbranch_scc0 .Lr22_end
	s_and_b32 s2, s15, 63
	s_lshr_b32 s3, s15, 6
	s_mul_i32 s14, s2, 0x80000
	s_add_u32 s8, s26, s14
	s_addc_u32 s9, s27, 0
	s_mul_i32 s14, s3, 0x80000
	s_add_u32 s10, s28, s14
	s_addc_u32 s11, s29, 0
	s_lshl_b32 s14, s2, 19
	s_lshl_b32 s6, s3, 9
	s_add_u32 s14, s14, s6
	s_add_u32 s20, s4, 0x6b7a100
	s_addc_u32 s21, s5, 0
	s_add_u32 s20, s20, s14
	s_addc_u32 s21, s21, 0
	s_sub_u32 s7, s2, 32
	s_lshr_b32 s7, s7, 3
	s_add_u32 s7, s7, 1
	s_cmp_lt_u32 s2, 32
	s_cselect_b32 s7, 0, s7
	s_mul_i32 s7, s7, 0x6000
	s_add_u32 s7, s7, s6
	s_add_u32 s22, s4, 0x6b40000
	s_addc_u32 s23, s5, 0
	s_add_u32 s22, s22, s7
	s_addc_u32 s23, s23, 0
	v_readfirstlane_b32 s12, v247
	s_lshl_b32 s12, s12, 12
	s_add_u32 m0, s12, 0x0
	v_mov_b32_e32 v0, 0
	global_load_lds_dwordx4 v248, s[8:9]
	v_mov_b32_e32 v1, 0
	s_add_u32 m0, s12, 0x400
	v_mov_b32_e32 v2, 0
	global_load_lds_dwordx4 v249, s[8:9]
	v_mov_b32_e32 v3, 0
	s_add_u32 m0, s12, 0x800
	v_mov_b32_e32 v4, 0
	global_load_lds_dwordx4 v250, s[8:9]
	v_mov_b32_e32 v5, 0
	s_add_u32 m0, s12, 0xc00
	v_mov_b32_e32 v6, 0
	global_load_lds_dwordx4 v251, s[8:9]
	v_mov_b32_e32 v7, 0
	s_add_u32 m0, s12, 0x8000
	v_mov_b32_e32 v8, 0
	global_load_lds_dwordx4 v248, s[10:11]
	v_mov_b32_e32 v9, 0
	s_add_u32 m0, s12, 0x8400
	v_mov_b32_e32 v10, 0
	global_load_lds_dwordx4 v249, s[10:11]
	v_mov_b32_e32 v11, 0
	s_add_u32 m0, s12, 0x8800
	v_mov_b32_e32 v12, 0
	global_load_lds_dwordx4 v250, s[10:11]
	v_mov_b32_e32 v13, 0
	s_add_u32 m0, s12, 0x8c00
	v_mov_b32_e32 v14, 0
	global_load_lds_dwordx4 v251, s[10:11]
	v_mov_b32_e32 v15, 0
	s_add_u32 s8, s8, 0x80
	s_addc_u32 s9, s9, 0
	s_add_u32 s10, s10, 0x80
	s_addc_u32 s11, s11, 0
	s_add_u32 m0, s12, 0x4000
	v_mov_b32_e32 v16, 0
	global_load_lds_dwordx4 v248, s[8:9]
	v_mov_b32_e32 v17, 0
	s_add_u32 m0, s12, 0x4400
	v_mov_b32_e32 v18, 0
	global_load_lds_dwordx4 v249, s[8:9]
	v_mov_b32_e32 v19, 0
	s_add_u32 m0, s12, 0x4800
	v_mov_b32_e32 v20, 0
	global_load_lds_dwordx4 v250, s[8:9]
	v_mov_b32_e32 v21, 0
	s_add_u32 m0, s12, 0x4c00
	v_mov_b32_e32 v22, 0
	global_load_lds_dwordx4 v251, s[8:9]
	v_mov_b32_e32 v23, 0
	s_add_u32 m0, s12, 0xc000
	v_mov_b32_e32 v24, 0
	global_load_lds_dwordx4 v248, s[10:11]
	v_mov_b32_e32 v25, 0
	s_add_u32 m0, s12, 0xc400
	v_mov_b32_e32 v26, 0
	global_load_lds_dwordx4 v249, s[10:11]
	v_mov_b32_e32 v27, 0
	s_add_u32 m0, s12, 0xc800
	v_mov_b32_e32 v28, 0
	global_load_lds_dwordx4 v250, s[10:11]
	v_mov_b32_e32 v29, 0
	s_add_u32 m0, s12, 0xcc00
	v_mov_b32_e32 v30, 0
	global_load_lds_dwordx4 v251, s[10:11]
	v_mov_b32_e32 v31, 0
	s_add_u32 s8, s8, 0x80
	s_addc_u32 s9, s9, 0
	s_add_u32 s10, s10, 0x80
	s_addc_u32 s11, s11, 0
	v_mov_b32_e32 v32, 0
	v_mov_b32_e32 v33, 0
	v_mov_b32_e32 v34, 0
	v_mov_b32_e32 v35, 0
	v_mov_b32_e32 v36, 0
	v_mov_b32_e32 v37, 0
	v_mov_b32_e32 v38, 0
	v_mov_b32_e32 v39, 0
	v_mov_b32_e32 v40, 0
	v_mov_b32_e32 v41, 0
	v_mov_b32_e32 v42, 0
	v_mov_b32_e32 v43, 0
	v_mov_b32_e32 v44, 0
	v_mov_b32_e32 v45, 0
	v_mov_b32_e32 v46, 0
	v_mov_b32_e32 v47, 0
	v_mov_b32_e32 v48, 0
	v_mov_b32_e32 v49, 0
	v_mov_b32_e32 v50, 0
	v_mov_b32_e32 v51, 0
	v_mov_b32_e32 v52, 0
	v_mov_b32_e32 v53, 0
	v_mov_b32_e32 v54, 0
	v_mov_b32_e32 v55, 0
	v_mov_b32_e32 v56, 0
	v_mov_b32_e32 v57, 0
	v_mov_b32_e32 v58, 0
	v_mov_b32_e32 v59, 0
	v_mov_b32_e32 v60, 0
	v_mov_b32_e32 v61, 0
	v_mov_b32_e32 v62, 0
	v_mov_b32_e32 v63, 0
	global_load_dword v201, v245, s[22:23] offset:0
	global_load_dword v202, v245, s[22:23] offset:64
	global_load_dword v203, v245, s[22:23] offset:128
	global_load_dword v204, v245, s[22:23] offset:192
	s_mov_b64 s[18:19], s[20:21]
	global_load_dword v129, v246, s[18:19] offset:0
	global_load_dword v130, v246, s[18:19] offset:64
	global_load_dword v131, v246, s[18:19] offset:128
	global_load_dword v132, v246, s[18:19] offset:192
	s_add_u32 s18, s18, 0x1000
	s_addc_u32 s19, s19, 0
	global_load_dword v133, v246, s[18:19] offset:0
	global_load_dword v134, v246, s[18:19] offset:64
	global_load_dword v135, v246, s[18:19] offset:128
	global_load_dword v136, v246, s[18:19] offset:192
	s_add_u32 s18, s18, 0x1000
	s_addc_u32 s19, s19, 0
	global_load_dword v137, v246, s[18:19] offset:0
	global_load_dword v138, v246, s[18:19] offset:64
	global_load_dword v139, v246, s[18:19] offset:128
	global_load_dword v140, v246, s[18:19] offset:192
	s_add_u32 s18, s18, 0x1000
	s_addc_u32 s19, s19, 0
	global_load_dword v141, v246, s[18:19] offset:0
	global_load_dword v142, v246, s[18:19] offset:64
	global_load_dword v143, v246, s[18:19] offset:128
	global_load_dword v144, v246, s[18:19] offset:192
	s_add_u32 s18, s18, 0xd000
	s_addc_u32 s19, s19, 0
	global_load_dword v145, v246, s[18:19] offset:0
	global_load_dword v146, v246, s[18:19] offset:64
	global_load_dword v147, v246, s[18:19] offset:128
	global_load_dword v148, v246, s[18:19] offset:192
	s_add_u32 s18, s18, 0x1000
	s_addc_u32 s19, s19, 0
	global_load_dword v149, v246, s[18:19] offset:0
	global_load_dword v150, v246, s[18:19] offset:64
	global_load_dword v151, v246, s[18:19] offset:128
	global_load_dword v152, v246, s[18:19] offset:192
	s_add_u32 s18, s18, 0x1000
	s_addc_u32 s19, s19, 0
	global_load_dword v153, v246, s[18:19] offset:0
	global_load_dword v154, v246, s[18:19] offset:64
	global_load_dword v155, v246, s[18:19] offset:128
	global_load_dword v156, v246, s[18:19] offset:192
	s_add_u32 s18, s18, 0x1000
	s_addc_u32 s19, s19, 0
	global_load_dword v157, v246, s[18:19] offset:0
	global_load_dword v158, v246, s[18:19] offset:64
	global_load_dword v159, v246, s[18:19] offset:128
	global_load_dword v160, v246, s[18:19] offset:192
	s_add_u32 s18, s18, 0xd000
	s_addc_u32 s19, s19, 0
	global_load_dword v161, v246, s[18:19] offset:0
	global_load_dword v170, v246, s[18:19] offset:64
	global_load_dword v171, v246, s[18:19] offset:128
	global_load_dword v172, v246, s[18:19] offset:192
	s_add_u32 s18, s18, 0x1000
	s_addc_u32 s19, s19, 0
	global_load_dword v173, v246, s[18:19] offset:0
	global_load_dword v174, v246, s[18:19] offset:64
	global_load_dword v175, v246, s[18:19] offset:128
	global_load_dword v176, v246, s[18:19] offset:192
	s_add_u32 s18, s18, 0x1000
	s_addc_u32 s19, s19, 0
	global_load_dword v177, v246, s[18:19] offset:0
	global_load_dword v178, v246, s[18:19] offset:64
	global_load_dword v179, v246, s[18:19] offset:128
	global_load_dword v180, v246, s[18:19] offset:192
	s_add_u32 s18, s18, 0x1000
	s_addc_u32 s19, s19, 0
	global_load_dword v181, v246, s[18:19] offset:0
	global_load_dword v182, v246, s[18:19] offset:64
	global_load_dword v183, v246, s[18:19] offset:128
	global_load_dword v184, v246, s[18:19] offset:192
	s_add_u32 s18, s18, 0xd000
	s_addc_u32 s19, s19, 0
	global_load_dword v185, v246, s[18:19] offset:0
	global_load_dword v186, v246, s[18:19] offset:64
	global_load_dword v187, v246, s[18:19] offset:128
	global_load_dword v188, v246, s[18:19] offset:192
	s_add_u32 s18, s18, 0x1000
	s_addc_u32 s19, s19, 0
	global_load_dword v189, v246, s[18:19] offset:0
	global_load_dword v190, v246, s[18:19] offset:64
	global_load_dword v191, v246, s[18:19] offset:128
	global_load_dword v192, v246, s[18:19] offset:192
	s_add_u32 s18, s18, 0x1000
	s_addc_u32 s19, s19, 0
	global_load_dword v193, v246, s[18:19] offset:0
	global_load_dword v194, v246, s[18:19] offset:64
	global_load_dword v195, v246, s[18:19] offset:128
	global_load_dword v196, v246, s[18:19] offset:192
	s_add_u32 s18, s18, 0x1000
	s_addc_u32 s19, s19, 0
	global_load_dword v197, v246, s[18:19] offset:0
	global_load_dword v198, v246, s[18:19] offset:64
	global_load_dword v199, v246, s[18:19] offset:128
	global_load_dword v200, v246, s[18:19] offset:192
	s_waitcnt vmcnt(63)
	s_barrier
	ds_read_b128 v[64:67], v252 offset:0
	ds_read_b128 v[96:99], v254 offset:32768
	ds_read_b128 v[100:103], v254 offset:34816
	ds_read_b128 v[104:107], v254 offset:36864
	ds_read_b128 v[108:111], v254 offset:38912
	ds_read_b128 v[68:71], v252 offset:2048
	ds_read_b128 v[72:75], v252 offset:4096
	ds_read_b128 v[76:79], v252 offset:6144
	ds_read_b128 v[80:83], v253 offset:0
	ds_read_b128 v[112:115], v255 offset:32768
	ds_read_b128 v[116:119], v255 offset:34816
	ds_read_b128 v[120:123], v255 offset:36864
	ds_read_b128 v[124:127], v255 offset:38912
	s_waitcnt lgkmcnt(11)
	v_mfma_f32_16x16x32_bf16 v[0:3], v[64:67], v[96:99], v[0:3]
	s_waitcnt lgkmcnt(10)
	v_mfma_f32_16x16x32_bf16 v[4:7], v[64:67], v[100:103], v[4:7]
	s_waitcnt lgkmcnt(9)
	v_mfma_f32_16x16x32_bf16 v[8:11], v[64:67], v[104:107], v[8:11]
	s_waitcnt lgkmcnt(8)
	v_mfma_f32_16x16x32_bf16 v[12:15], v[64:67], v[108:111], v[12:15]
	ds_read_b128 v[84:87], v253 offset:2048
	ds_read_b128 v[88:91], v253 offset:4096
	ds_read_b128 v[92:95], v253 offset:6144
	s_waitcnt lgkmcnt(10)
	v_mfma_f32_16x16x32_bf16 v[16:19], v[68:71], v[96:99], v[16:19]
	v_mfma_f32_16x16x32_bf16 v[20:23], v[68:71], v[100:103], v[20:23]
	v_mfma_f32_16x16x32_bf16 v[24:27], v[68:71], v[104:107], v[24:27]
	v_mfma_f32_16x16x32_bf16 v[28:31], v[68:71], v[108:111], v[28:31]
	s_waitcnt lgkmcnt(0)
	s_barrier
	s_add_u32 m0, s12, 0x0
	v_mfma_f32_16x16x32_bf16 v[32:35], v[72:75], v[96:99], v[32:35]
	global_load_lds_dwordx4 v248, s[8:9]
	s_add_u32 m0, s12, 0x400
	v_mfma_f32_16x16x32_bf16 v[36:39], v[72:75], v[100:103], v[36:39]
	global_load_lds_dwordx4 v249, s[8:9]
	s_add_u32 m0, s12, 0x800
	v_mfma_f32_16x16x32_bf16 v[40:43], v[72:75], v[104:107], v[40:43]
	global_load_lds_dwordx4 v250, s[8:9]
	s_add_u32 m0, s12, 0xc00
	v_mfma_f32_16x16x32_bf16 v[44:47], v[72:75], v[108:111], v[44:47]
	global_load_lds_dwordx4 v251, s[8:9]
	s_add_u32 m0, s12, 0x8000
	v_mfma_f32_16x16x32_bf16 v[48:51], v[76:79], v[96:99], v[48:51]
	global_load_lds_dwordx4 v248, s[10:11]
	s_add_u32 m0, s12, 0x8400
	v_mfma_f32_16x16x32_bf16 v[52:55], v[76:79], v[100:103], v[52:55]
	global_load_lds_dwordx4 v249, s[10:11]
	s_add_u32 m0, s12, 0x8800
	v_mfma_f32_16x16x32_bf16 v[56:59], v[76:79], v[104:107], v[56:59]
	global_load_lds_dwordx4 v250, s[10:11]
	s_add_u32 m0, s12, 0x8c00
	v_mfma_f32_16x16x32_bf16 v[60:63], v[76:79], v[108:111], v[60:63]
	global_load_lds_dwordx4 v251, s[10:11]
	s_add_u32 s8, s8, 0x80
	s_addc_u32 s9, s9, 0
	s_add_u32 s10, s10, 0x80
	s_addc_u32 s11, s11, 0
	s_waitcnt vmcnt(63)
	s_barrier
	ds_read_b128 v[64:67], v252 offset:16384
	ds_read_b128 v[96:99], v254 offset:49152
	ds_read_b128 v[100:103], v254 offset:51200
	ds_read_b128 v[104:107], v254 offset:53248
	ds_read_b128 v[108:111], v254 offset:55296
	ds_read_b128 v[68:71], v252 offset:18432
	ds_read_b128 v[72:75], v252 offset:20480
	ds_read_b128 v[76:79], v252 offset:22528
	v_mfma_f32_16x16x32_bf16 v[0:3], v[80:83], v[112:115], v[0:3]
	v_mfma_f32_16x16x32_bf16 v[4:7], v[80:83], v[116:119], v[4:7]
	v_mfma_f32_16x16x32_bf16 v[8:11], v[80:83], v[120:123], v[8:11]
	v_mfma_f32_16x16x32_bf16 v[12:15], v[80:83], v[124:127], v[12:15]
	v_mfma_f32_16x16x32_bf16 v[16:19], v[84:87], v[112:115], v[16:19]
	v_mfma_f32_16x16x32_bf16 v[20:23], v[84:87], v[116:119], v[20:23]
	v_mfma_f32_16x16x32_bf16 v[24:27], v[84:87], v[120:123], v[24:27]
	v_mfma_f32_16x16x32_bf16 v[28:31], v[84:87], v[124:127], v[28:31]
	v_mfma_f32_16x16x32_bf16 v[32:35], v[88:91], v[112:115], v[32:35]
	v_mfma_f32_16x16x32_bf16 v[36:39], v[88:91], v[116:119], v[36:39]
	v_mfma_f32_16x16x32_bf16 v[40:43], v[88:91], v[120:123], v[40:43]
	v_mfma_f32_16x16x32_bf16 v[44:47], v[88:91], v[124:127], v[44:47]
	v_mfma_f32_16x16x32_bf16 v[48:51], v[92:95], v[112:115], v[48:51]
	v_mfma_f32_16x16x32_bf16 v[52:55], v[92:95], v[116:119], v[52:55]
	v_mfma_f32_16x16x32_bf16 v[56:59], v[92:95], v[120:123], v[56:59]
	v_mfma_f32_16x16x32_bf16 v[60:63], v[92:95], v[124:127], v[60:63]
	ds_read_b128 v[80:83], v253 offset:16384
	ds_read_b128 v[112:115], v255 offset:49152
	ds_read_b128 v[116:119], v255 offset:51200
	ds_read_b128 v[120:123], v255 offset:53248
	ds_read_b128 v[124:127], v255 offset:55296
	ds_read_b128 v[84:87], v253 offset:18432
	ds_read_b128 v[88:91], v253 offset:20480
	ds_read_b128 v[92:95], v253 offset:22528
	s_waitcnt lgkmcnt(14)
	v_mfma_f32_16x16x32_bf16 v[0:3], v[64:67], v[96:99], v[0:3]
	s_waitcnt lgkmcnt(13)
	v_mfma_f32_16x16x32_bf16 v[4:7], v[64:67], v[100:103], v[4:7]
	s_waitcnt lgkmcnt(12)
	v_mfma_f32_16x16x32_bf16 v[8:11], v[64:67], v[104:107], v[8:11]
	s_waitcnt lgkmcnt(11)
	v_mfma_f32_16x16x32_bf16 v[12:15], v[64:67], v[108:111], v[12:15]
	s_waitcnt lgkmcnt(10)
	v_mfma_f32_16x16x32_bf16 v[16:19], v[68:71], v[96:99], v[16:19]
	v_mfma_f32_16x16x32_bf16 v[20:23], v[68:71], v[100:103], v[20:23]
	v_mfma_f32_16x16x32_bf16 v[24:27], v[68:71], v[104:107], v[24:27]
	v_mfma_f32_16x16x32_bf16 v[28:31], v[68:71], v[108:111], v[28:31]
	s_waitcnt lgkmcnt(0)
	s_barrier
	s_add_u32 m0, s12, 0x4000
	v_mfma_f32_16x16x32_bf16 v[32:35], v[72:75], v[96:99], v[32:35]
	global_load_lds_dwordx4 v248, s[8:9]
	s_add_u32 m0, s12, 0x4400
	v_mfma_f32_16x16x32_bf16 v[36:39], v[72:75], v[100:103], v[36:39]
	global_load_lds_dwordx4 v249, s[8:9]
	s_add_u32 m0, s12, 0x4800
	v_mfma_f32_16x16x32_bf16 v[40:43], v[72:75], v[104:107], v[40:43]
	global_load_lds_dwordx4 v250, s[8:9]
	s_add_u32 m0, s12, 0x4c00
	v_mfma_f32_16x16x32_bf16 v[44:47], v[72:75], v[108:111], v[44:47]
	global_load_lds_dwordx4 v251, s[8:9]
	s_add_u32 m0, s12, 0xc000
	v_mfma_f32_16x16x32_bf16 v[48:51], v[76:79], v[96:99], v[48:51]
	global_load_lds_dwordx4 v248, s[10:11]
	s_add_u32 m0, s12, 0xc400
	v_mfma_f32_16x16x32_bf16 v[52:55], v[76:79], v[100:103], v[52:55]
	global_load_lds_dwordx4 v249, s[10:11]
	s_add_u32 m0, s12, 0xc800
	v_mfma_f32_16x16x32_bf16 v[56:59], v[76:79], v[104:107], v[56:59]
	global_load_lds_dwordx4 v250, s[10:11]
	s_add_u32 m0, s12, 0xcc00
	v_mfma_f32_16x16x32_bf16 v[60:63], v[76:79], v[108:111], v[60:63]
	global_load_lds_dwordx4 v251, s[10:11]
	s_add_u32 s8, s8, 0x80
	s_addc_u32 s9, s9, 0
	s_add_u32 s10, s10, 0x80
	s_addc_u32 s11, s11, 0
	s_mov_b32 s13, 14

.Lr25_tile:
	s_cmp_lt_u32 s15, 0x200
	s_cbranch_scc0 .Lr25_end
	s_and_b32 s2, s15, 63
	s_lshr_b32 s3, s15, 6
	s_mul_i32 s14, s2, 0xb0000
	s_add_u32 s8, s26, s14
	s_addc_u32 s9, s27, 0
	s_mul_i32 s14, s3, 0xb0000
	s_add_u32 s10, s28, s14
	s_addc_u32 s11, s29, 0
	s_lshl_b32 s14, s2, 19
	s_lshl_b32 s6, s3, 9
	s_add_u32 s14, s14, s6
	s_add_u32 s20, s4, 0x6b7a100
	s_addc_u32 s21, s5, 0
	s_add_u32 s20, s20, s14
	s_addc_u32 s21, s21, 0
	s_sub_u32 s7, s2, 32
	s_lshr_b32 s7, s7, 3
	s_add_u32 s7, s7, 1
	s_cmp_lt_u32 s2, 32
	s_cselect_b32 s7, 0, s7
	s_mul_i32 s7, s7, 0x6000
	s_add_u32 s7, s7, s6
	s_add_u32 s22, s4, 0x6b43000
	s_addc_u32 s23, s5, 0
	s_add_u32 s22, s22, s7
	s_addc_u32 s23, s23, 0
	v_readfirstlane_b32 s12, v247
	s_lshl_b32 s12, s12, 12
	s_add_u32 m0, s12, 0x0
	v_mov_b32_e32 v0, 0
	global_load_lds_dwordx4 v248, s[8:9]
	v_mov_b32_e32 v1, 0
	s_add_u32 m0, s12, 0x400
	v_mov_b32_e32 v2, 0
	global_load_lds_dwordx4 v249, s[8:9]
	v_mov_b32_e32 v3, 0
	s_add_u32 m0, s12, 0x800
	v_mov_b32_e32 v4, 0
	global_load_lds_dwordx4 v250, s[8:9]
	v_mov_b32_e32 v5, 0
	s_add_u32 m0, s12, 0xc00
	v_mov_b32_e32 v6, 0
	global_load_lds_dwordx4 v251, s[8:9]
	v_mov_b32_e32 v7, 0
	s_add_u32 m0, s12, 0x8000
	v_mov_b32_e32 v8, 0
	global_load_lds_dwordx4 v248, s[10:11]
	v_mov_b32_e32 v9, 0
	s_add_u32 m0, s12, 0x8400
	v_mov_b32_e32 v10, 0
	global_load_lds_dwordx4 v249, s[10:11]
	v_mov_b32_e32 v11, 0
	s_add_u32 m0, s12, 0x8800
	v_mov_b32_e32 v12, 0
	global_load_lds_dwordx4 v250, s[10:11]
	v_mov_b32_e32 v13, 0
	s_add_u32 m0, s12, 0x8c00
	v_mov_b32_e32 v14, 0
	global_load_lds_dwordx4 v251, s[10:11]
	v_mov_b32_e32 v15, 0
	s_add_u32 s8, s8, 0x80
	s_addc_u32 s9, s9, 0
	s_add_u32 s10, s10, 0x80
	s_addc_u32 s11, s11, 0
	s_add_u32 m0, s12, 0x4000
	v_mov_b32_e32 v16, 0
	global_load_lds_dwordx4 v248, s[8:9]
	v_mov_b32_e32 v17, 0
	s_add_u32 m0, s12, 0x4400
	v_mov_b32_e32 v18, 0
	global_load_lds_dwordx4 v249, s[8:9]
	v_mov_b32_e32 v19, 0
	s_add_u32 m0, s12, 0x4800
	v_mov_b32_e32 v20, 0
	global_load_lds_dwordx4 v250, s[8:9]
	v_mov_b32_e32 v21, 0
	s_add_u32 m0, s12, 0x4c00
	v_mov_b32_e32 v22, 0
	global_load_lds_dwordx4 v251, s[8:9]
	v_mov_b32_e32 v23, 0
	s_add_u32 m0, s12, 0xc000
	v_mov_b32_e32 v24, 0
	global_load_lds_dwordx4 v248, s[10:11]
	v_mov_b32_e32 v25, 0
	s_add_u32 m0, s12, 0xc400
	v_mov_b32_e32 v26, 0
	global_load_lds_dwordx4 v249, s[10:11]
	v_mov_b32_e32 v27, 0
	s_add_u32 m0, s12, 0xc800
	v_mov_b32_e32 v28, 0
	global_load_lds_dwordx4 v250, s[10:11]
	v_mov_b32_e32 v29, 0
	s_add_u32 m0, s12, 0xcc00
	v_mov_b32_e32 v30, 0
	global_load_lds_dwordx4 v251, s[10:11]
	v_mov_b32_e32 v31, 0
	s_add_u32 s8, s8, 0x80
	s_addc_u32 s9, s9, 0
	s_add_u32 s10, s10, 0x80
	s_addc_u32 s11, s11, 0
	v_mov_b32_e32 v32, 0
	v_mov_b32_e32 v33, 0
	v_mov_b32_e32 v34, 0
	v_mov_b32_e32 v35, 0
	v_mov_b32_e32 v36, 0
	v_mov_b32_e32 v37, 0
	v_mov_b32_e32 v38, 0
	v_mov_b32_e32 v39, 0
	v_mov_b32_e32 v40, 0
	v_mov_b32_e32 v41, 0
	v_mov_b32_e32 v42, 0
	v_mov_b32_e32 v43, 0
	v_mov_b32_e32 v44, 0
	v_mov_b32_e32 v45, 0
	v_mov_b32_e32 v46, 0
	v_mov_b32_e32 v47, 0
	v_mov_b32_e32 v48, 0
	v_mov_b32_e32 v49, 0
	v_mov_b32_e32 v50, 0
	v_mov_b32_e32 v51, 0
	v_mov_b32_e32 v52, 0
	v_mov_b32_e32 v53, 0
	v_mov_b32_e32 v54, 0
	v_mov_b32_e32 v55, 0
	v_mov_b32_e32 v56, 0
	v_mov_b32_e32 v57, 0
	v_mov_b32_e32 v58, 0
	v_mov_b32_e32 v59, 0
	v_mov_b32_e32 v60, 0
	v_mov_b32_e32 v61, 0
	v_mov_b32_e32 v62, 0
	v_mov_b32_e32 v63, 0
	global_load_dword v201, v245, s[22:23] offset:0
	global_load_dword v202, v245, s[22:23] offset:64
	global_load_dword v203, v245, s[22:23] offset:128
	global_load_dword v204, v245, s[22:23] offset:192
	s_mov_b64 s[18:19], s[20:21]
	global_load_dword v129, v246, s[18:19] offset:0
	global_load_dword v130, v246, s[18:19] offset:64
	global_load_dword v131, v246, s[18:19] offset:128
	global_load_dword v132, v246, s[18:19] offset:192
	s_add_u32 s18, s18, 0x1000
	s_addc_u32 s19, s19, 0
	global_load_dword v133, v246, s[18:19] offset:0
	global_load_dword v134, v246, s[18:19] offset:64
	global_load_dword v135, v246, s[18:19] offset:128
	global_load_dword v136, v246, s[18:19] offset:192
	s_add_u32 s18, s18, 0x1000
	s_addc_u32 s19, s19, 0
	global_load_dword v137, v246, s[18:19] offset:0
	global_load_dword v138, v246, s[18:19] offset:64
	global_load_dword v139, v246, s[18:19] offset:128
	global_load_dword v140, v246, s[18:19] offset:192
	s_add_u32 s18, s18, 0x1000
	s_addc_u32 s19, s19, 0
	global_load_dword v141, v246, s[18:19] offset:0
	global_load_dword v142, v246, s[18:19] offset:64
	global_load_dword v143, v246, s[18:19] offset:128
	global_load_dword v144, v246, s[18:19] offset:192
	s_add_u32 s18, s18, 0xd000
	s_addc_u32 s19, s19, 0
	global_load_dword v145, v246, s[18:19] offset:0
	global_load_dword v146, v246, s[18:19] offset:64
	global_load_dword v147, v246, s[18:19] offset:128
	global_load_dword v148, v246, s[18:19] offset:192
	s_add_u32 s18, s18, 0x1000
	s_addc_u32 s19, s19, 0
	global_load_dword v149, v246, s[18:19] offset:0
	global_load_dword v150, v246, s[18:19] offset:64
	global_load_dword v151, v246, s[18:19] offset:128
	global_load_dword v152, v246, s[18:19] offset:192
	s_add_u32 s18, s18, 0x1000
	s_addc_u32 s19, s19, 0
	global_load_dword v153, v246, s[18:19] offset:0
	global_load_dword v154, v246, s[18:19] offset:64
	global_load_dword v155, v246, s[18:19] offset:128
	global_load_dword v156, v246, s[18:19] offset:192
	s_add_u32 s18, s18, 0x1000
	s_addc_u32 s19, s19, 0
	global_load_dword v157, v246, s[18:19] offset:0
	global_load_dword v158, v246, s[18:19] offset:64
	global_load_dword v159, v246, s[18:19] offset:128
	global_load_dword v160, v246, s[18:19] offset:192
	s_add_u32 s18, s18, 0xd000
	s_addc_u32 s19, s19, 0
	global_load_dword v161, v246, s[18:19] offset:0
	global_load_dword v170, v246, s[18:19] offset:64
	global_load_dword v171, v246, s[18:19] offset:128
	global_load_dword v172, v246, s[18:19] offset:192
	s_add_u32 s18, s18, 0x1000
	s_addc_u32 s19, s19, 0
	global_load_dword v173, v246, s[18:19] offset:0
	global_load_dword v174, v246, s[18:19] offset:64
	global_load_dword v175, v246, s[18:19] offset:128
	global_load_dword v176, v246, s[18:19] offset:192
	s_add_u32 s18, s18, 0x1000
	s_addc_u32 s19, s19, 0
	global_load_dword v177, v246, s[18:19] offset:0
	global_load_dword v178, v246, s[18:19] offset:64
	global_load_dword v179, v246, s[18:19] offset:128
	global_load_dword v180, v246, s[18:19] offset:192
	s_add_u32 s18, s18, 0x1000
	s_addc_u32 s19, s19, 0
	global_load_dword v181, v246, s[18:19] offset:0
	global_load_dword v182, v246, s[18:19] offset:64
	global_load_dword v183, v246, s[18:19] offset:128
	global_load_dword v184, v246, s[18:19] offset:192
	s_add_u32 s18, s18, 0xd000
	s_addc_u32 s19, s19, 0
	global_load_dword v185, v246, s[18:19] offset:0
	global_load_dword v186, v246, s[18:19] offset:64
	global_load_dword v187, v246, s[18:19] offset:128
	global_load_dword v188, v246, s[18:19] offset:192
	s_add_u32 s18, s18, 0x1000
	s_addc_u32 s19, s19, 0
	global_load_dword v189, v246, s[18:19] offset:0
	global_load_dword v190, v246, s[18:19] offset:64
	global_load_dword v191, v246, s[18:19] offset:128
	global_load_dword v192, v246, s[18:19] offset:192
	s_add_u32 s18, s18, 0x1000
	s_addc_u32 s19, s19, 0
	global_load_dword v193, v246, s[18:19] offset:0
	global_load_dword v194, v246, s[18:19] offset:64
	global_load_dword v195, v246, s[18:19] offset:128
	global_load_dword v196, v246, s[18:19] offset:192
	s_add_u32 s18, s18, 0x1000
	s_addc_u32 s19, s19, 0
	global_load_dword v197, v246, s[18:19] offset:0
	global_load_dword v198, v246, s[18:19] offset:64
	global_load_dword v199, v246, s[18:19] offset:128
	global_load_dword v200, v246, s[18:19] offset:192
	s_waitcnt vmcnt(63)
	s_barrier
	ds_read_b128 v[64:67], v252 offset:0
	ds_read_b128 v[96:99], v254 offset:32768
	ds_read_b128 v[100:103], v254 offset:34816
	ds_read_b128 v[104:107], v254 offset:36864
	ds_read_b128 v[108:111], v254 offset:38912
	ds_read_b128 v[68:71], v252 offset:2048
	ds_read_b128 v[72:75], v252 offset:4096
	ds_read_b128 v[76:79], v252 offset:6144
	ds_read_b128 v[80:83], v253 offset:0
	ds_read_b128 v[112:115], v255 offset:32768
	ds_read_b128 v[116:119], v255 offset:34816
	ds_read_b128 v[120:123], v255 offset:36864
	ds_read_b128 v[124:127], v255 offset:38912
	s_waitcnt lgkmcnt(11)
	v_mfma_f32_16x16x32_bf16 v[0:3], v[64:67], v[96:99], v[0:3]
	s_waitcnt lgkmcnt(10)
	v_mfma_f32_16x16x32_bf16 v[4:7], v[64:67], v[100:103], v[4:7]
	s_waitcnt lgkmcnt(9)
	v_mfma_f32_16x16x32_bf16 v[8:11], v[64:67], v[104:107], v[8:11]
	s_waitcnt lgkmcnt(8)
	v_mfma_f32_16x16x32_bf16 v[12:15], v[64:67], v[108:111], v[12:15]
	ds_read_b128 v[84:87], v253 offset:2048
	ds_read_b128 v[88:91], v253 offset:4096
	ds_read_b128 v[92:95], v253 offset:6144
	s_waitcnt lgkmcnt(10)
	v_mfma_f32_16x16x32_bf16 v[16:19], v[68:71], v[96:99], v[16:19]
	v_mfma_f32_16x16x32_bf16 v[20:23], v[68:71], v[100:103], v[20:23]
	v_mfma_f32_16x16x32_bf16 v[24:27], v[68:71], v[104:107], v[24:27]
	v_mfma_f32_16x16x32_bf16 v[28:31], v[68:71], v[108:111], v[28:31]
	s_waitcnt lgkmcnt(0)
	s_barrier
	s_add_u32 m0, s12, 0x0
	v_mfma_f32_16x16x32_bf16 v[32:35], v[72:75], v[96:99], v[32:35]
	global_load_lds_dwordx4 v248, s[8:9]
	s_add_u32 m0, s12, 0x400
	v_mfma_f32_16x16x32_bf16 v[36:39], v[72:75], v[100:103], v[36:39]
	global_load_lds_dwordx4 v249, s[8:9]
	s_add_u32 m0, s12, 0x800
	v_mfma_f32_16x16x32_bf16 v[40:43], v[72:75], v[104:107], v[40:43]
	global_load_lds_dwordx4 v250, s[8:9]
	s_add_u32 m0, s12, 0xc00
	v_mfma_f32_16x16x32_bf16 v[44:47], v[72:75], v[108:111], v[44:47]
	global_load_lds_dwordx4 v251, s[8:9]
	s_add_u32 m0, s12, 0x8000
	v_mfma_f32_16x16x32_bf16 v[48:51], v[76:79], v[96:99], v[48:51]
	global_load_lds_dwordx4 v248, s[10:11]
	s_add_u32 m0, s12, 0x8400
	v_mfma_f32_16x16x32_bf16 v[52:55], v[76:79], v[100:103], v[52:55]
	global_load_lds_dwordx4 v249, s[10:11]
	s_add_u32 m0, s12, 0x8800
	v_mfma_f32_16x16x32_bf16 v[56:59], v[76:79], v[104:107], v[56:59]
	global_load_lds_dwordx4 v250, s[10:11]
	s_add_u32 m0, s12, 0x8c00
	v_mfma_f32_16x16x32_bf16 v[60:63], v[76:79], v[108:111], v[60:63]
	global_load_lds_dwordx4 v251, s[10:11]
	s_add_u32 s8, s8, 0x80
	s_addc_u32 s9, s9, 0
	s_add_u32 s10, s10, 0x80
	s_addc_u32 s11, s11, 0
	s_waitcnt vmcnt(63)
	s_barrier
	ds_read_b128 v[64:67], v252 offset:16384
	ds_read_b128 v[96:99], v254 offset:49152
	ds_read_b128 v[100:103], v254 offset:51200
	ds_read_b128 v[104:107], v254 offset:53248
	ds_read_b128 v[108:111], v254 offset:55296
	ds_read_b128 v[68:71], v252 offset:18432
	ds_read_b128 v[72:75], v252 offset:20480
	ds_read_b128 v[76:79], v252 offset:22528
	v_mfma_f32_16x16x32_bf16 v[0:3], v[80:83], v[112:115], v[0:3]
	v_mfma_f32_16x16x32_bf16 v[4:7], v[80:83], v[116:119], v[4:7]
	v_mfma_f32_16x16x32_bf16 v[8:11], v[80:83], v[120:123], v[8:11]
	v_mfma_f32_16x16x32_bf16 v[12:15], v[80:83], v[124:127], v[12:15]
	v_mfma_f32_16x16x32_bf16 v[16:19], v[84:87], v[112:115], v[16:19]
	v_mfma_f32_16x16x32_bf16 v[20:23], v[84:87], v[116:119], v[20:23]
	v_mfma_f32_16x16x32_bf16 v[24:27], v[84:87], v[120:123], v[24:27]
	v_mfma_f32_16x16x32_bf16 v[28:31], v[84:87], v[124:127], v[28:31]
	v_mfma_f32_16x16x32_bf16 v[32:35], v[88:91], v[112:115], v[32:35]
	v_mfma_f32_16x16x32_bf16 v[36:39], v[88:91], v[116:119], v[36:39]
	v_mfma_f32_16x16x32_bf16 v[40:43], v[88:91], v[120:123], v[40:43]
	v_mfma_f32_16x16x32_bf16 v[44:47], v[88:91], v[124:127], v[44:47]
	v_mfma_f32_16x16x32_bf16 v[48:51], v[92:95], v[112:115], v[48:51]
	v_mfma_f32_16x16x32_bf16 v[52:55], v[92:95], v[116:119], v[52:55]
	v_mfma_f32_16x16x32_bf16 v[56:59], v[92:95], v[120:123], v[56:59]
	v_mfma_f32_16x16x32_bf16 v[60:63], v[92:95], v[124:127], v[60:63]
	ds_read_b128 v[80:83], v253 offset:16384
	ds_read_b128 v[112:115], v255 offset:49152
	ds_read_b128 v[116:119], v255 offset:51200
	ds_read_b128 v[120:123], v255 offset:53248
	ds_read_b128 v[124:127], v255 offset:55296
	ds_read_b128 v[84:87], v253 offset:18432
	ds_read_b128 v[88:91], v253 offset:20480
	ds_read_b128 v[92:95], v253 offset:22528
	s_waitcnt lgkmcnt(14)
	v_mfma_f32_16x16x32_bf16 v[0:3], v[64:67], v[96:99], v[0:3]
	s_waitcnt lgkmcnt(13)
	v_mfma_f32_16x16x32_bf16 v[4:7], v[64:67], v[100:103], v[4:7]
	s_waitcnt lgkmcnt(12)
	v_mfma_f32_16x16x32_bf16 v[8:11], v[64:67], v[104:107], v[8:11]
	s_waitcnt lgkmcnt(11)
	v_mfma_f32_16x16x32_bf16 v[12:15], v[64:67], v[108:111], v[12:15]
	s_waitcnt lgkmcnt(10)
	v_mfma_f32_16x16x32_bf16 v[16:19], v[68:71], v[96:99], v[16:19]
	v_mfma_f32_16x16x32_bf16 v[20:23], v[68:71], v[100:103], v[20:23]
	v_mfma_f32_16x16x32_bf16 v[24:27], v[68:71], v[104:107], v[24:27]
	v_mfma_f32_16x16x32_bf16 v[28:31], v[68:71], v[108:111], v[28:31]
	s_waitcnt lgkmcnt(0)
	s_barrier
	s_add_u32 m0, s12, 0x4000
	v_mfma_f32_16x16x32_bf16 v[32:35], v[72:75], v[96:99], v[32:35]
	global_load_lds_dwordx4 v248, s[8:9]
	s_add_u32 m0, s12, 0x4400
	v_mfma_f32_16x16x32_bf16 v[36:39], v[72:75], v[100:103], v[36:39]
	global_load_lds_dwordx4 v249, s[8:9]
	s_add_u32 m0, s12, 0x4800
	v_mfma_f32_16x16x32_bf16 v[40:43], v[72:75], v[104:107], v[40:43]
	global_load_lds_dwordx4 v250, s[8:9]
	s_add_u32 m0, s12, 0x4c00
	v_mfma_f32_16x16x32_bf16 v[44:47], v[72:75], v[108:111], v[44:47]
	global_load_lds_dwordx4 v251, s[8:9]
	s_add_u32 m0, s12, 0xc000
	v_mfma_f32_16x16x32_bf16 v[48:51], v[76:79], v[96:99], v[48:51]
	global_load_lds_dwordx4 v248, s[10:11]
	s_add_u32 m0, s12, 0xc400
	v_mfma_f32_16x16x32_bf16 v[52:55], v[76:79], v[100:103], v[52:55]
	global_load_lds_dwordx4 v249, s[10:11]
	s_add_u32 m0, s12, 0xc800
	v_mfma_f32_16x16x32_bf16 v[56:59], v[76:79], v[104:107], v[56:59]
	global_load_lds_dwordx4 v250, s[10:11]
	s_add_u32 m0, s12, 0xcc00
	v_mfma_f32_16x16x32_bf16 v[60:63], v[76:79], v[108:111], v[60:63]
	global_load_lds_dwordx4 v251, s[10:11]
	s_add_u32 s8, s8, 0x80
	s_addc_u32 s9, s9, 0
	s_add_u32 s10, s10, 0x80
	s_addc_u32 s11, s11, 0
	s_mov_b32 s13, 20

.Lr29_tile:
	s_cmp_lt_u32 s15, 0x200
	s_cbranch_scc0 .Lr29_end
	s_and_b32 s2, s15, 63
	s_lshr_b32 s3, s15, 6
	s_mul_i32 s14, s2, 0x40000
	s_add_u32 s8, s26, s14
	s_addc_u32 s9, s27, 0
	s_mul_i32 s14, s3, 0x40000
	s_add_u32 s10, s28, s14
	s_addc_u32 s11, s29, 0
	s_lshl_b32 s14, s2, 19
	s_lshl_b32 s6, s3, 9
	s_add_u32 s14, s14, s6
	s_add_u32 s20, s4, 0x6b7a100
	s_addc_u32 s21, s5, 0
	s_add_u32 s20, s20, s14
	s_addc_u32 s21, s21, 0
	s_sub_u32 s7, s2, 32
	s_lshr_b32 s7, s7, 3
	s_add_u32 s7, s7, 1
	s_cmp_lt_u32 s2, 32
	s_cselect_b32 s7, 0, s7
	s_mul_i32 s7, s7, 0x6000
	s_add_u32 s7, s7, s6
	s_add_u32 s22, s4, 0x6b5e000
	s_addc_u32 s23, s5, 0
	s_add_u32 s22, s22, s7
	s_addc_u32 s23, s23, 0
	s_add_u32 s30, s24, 0x1000
	s_addc_u32 s31, s25, 0
	s_add_u32 s30, s30, s6
	s_addc_u32 s31, s31, 0
	v_readfirstlane_b32 s12, v247
	s_lshl_b32 s12, s12, 12
	s_add_u32 m0, s12, 0x0
	v_mov_b32_e32 v0, 0
	global_load_lds_dwordx4 v248, s[8:9]
	v_mov_b32_e32 v1, 0
	s_add_u32 m0, s12, 0x400
	v_mov_b32_e32 v2, 0
	global_load_lds_dwordx4 v249, s[8:9]
	v_mov_b32_e32 v3, 0
	s_add_u32 m0, s12, 0x800
	v_mov_b32_e32 v4, 0
	global_load_lds_dwordx4 v250, s[8:9]
	v_mov_b32_e32 v5, 0
	s_add_u32 m0, s12, 0xc00
	v_mov_b32_e32 v6, 0
	global_load_lds_dwordx4 v251, s[8:9]
	v_mov_b32_e32 v7, 0
	s_add_u32 m0, s12, 0x8000
	v_mov_b32_e32 v8, 0
	global_load_lds_dwordx4 v248, s[10:11]
	v_mov_b32_e32 v9, 0
	s_add_u32 m0, s12, 0x8400
	v_mov_b32_e32 v10, 0
	global_load_lds_dwordx4 v249, s[10:11]
	v_mov_b32_e32 v11, 0
	s_add_u32 m0, s12, 0x8800
	v_mov_b32_e32 v12, 0
	global_load_lds_dwordx4 v250, s[10:11]
	v_mov_b32_e32 v13, 0
	s_add_u32 m0, s12, 0x8c00
	v_mov_b32_e32 v14, 0
	global_load_lds_dwordx4 v251, s[10:11]
	v_mov_b32_e32 v15, 0
	s_add_u32 s8, s8, 0x80
	s_addc_u32 s9, s9, 0
	s_add_u32 s10, s10, 0x80
	s_addc_u32 s11, s11, 0
	s_add_u32 m0, s12, 0x4000
	v_mov_b32_e32 v16, 0
	global_load_lds_dwordx4 v248, s[8:9]
	v_mov_b32_e32 v17, 0
	s_add_u32 m0, s12, 0x4400
	v_mov_b32_e32 v18, 0
	global_load_lds_dwordx4 v249, s[8:9]
	v_mov_b32_e32 v19, 0
	s_add_u32 m0, s12, 0x4800
	v_mov_b32_e32 v20, 0
	global_load_lds_dwordx4 v250, s[8:9]
	v_mov_b32_e32 v21, 0
	s_add_u32 m0, s12, 0x4c00
	v_mov_b32_e32 v22, 0
	global_load_lds_dwordx4 v251, s[8:9]
	v_mov_b32_e32 v23, 0
	s_add_u32 m0, s12, 0xc000
	v_mov_b32_e32 v24, 0
	global_load_lds_dwordx4 v248, s[10:11]
	v_mov_b32_e32 v25, 0
	s_add_u32 m0, s12, 0xc400
	v_mov_b32_e32 v26, 0
	global_load_lds_dwordx4 v249, s[10:11]
	v_mov_b32_e32 v27, 0
	s_add_u32 m0, s12, 0xc800
	v_mov_b32_e32 v28, 0
	global_load_lds_dwordx4 v250, s[10:11]
	v_mov_b32_e32 v29, 0
	s_add_u32 m0, s12, 0xcc00
	v_mov_b32_e32 v30, 0
	global_load_lds_dwordx4 v251, s[10:11]
	v_mov_b32_e32 v31, 0
	s_add_u32 s8, s8, 0x80
	s_addc_u32 s9, s9, 0
	s_add_u32 s10, s10, 0x80
	s_addc_u32 s11, s11, 0
	v_mov_b32_e32 v32, 0
	v_mov_b32_e32 v33, 0
	v_mov_b32_e32 v34, 0
	v_mov_b32_e32 v35, 0
	v_mov_b32_e32 v36, 0
	v_mov_b32_e32 v37, 0
	v_mov_b32_e32 v38, 0
	v_mov_b32_e32 v39, 0
	v_mov_b32_e32 v40, 0
	v_mov_b32_e32 v41, 0
	v_mov_b32_e32 v42, 0
	v_mov_b32_e32 v43, 0
	v_mov_b32_e32 v44, 0
	v_mov_b32_e32 v45, 0
	v_mov_b32_e32 v46, 0
	v_mov_b32_e32 v47, 0
	v_mov_b32_e32 v48, 0
	v_mov_b32_e32 v49, 0
	v_mov_b32_e32 v50, 0
	v_mov_b32_e32 v51, 0
	v_mov_b32_e32 v52, 0
	v_mov_b32_e32 v53, 0
	v_mov_b32_e32 v54, 0
	v_mov_b32_e32 v55, 0
	v_mov_b32_e32 v56, 0
	v_mov_b32_e32 v57, 0
	v_mov_b32_e32 v58, 0
	v_mov_b32_e32 v59, 0
	v_mov_b32_e32 v60, 0
	v_mov_b32_e32 v61, 0
	v_mov_b32_e32 v62, 0
	v_mov_b32_e32 v63, 0
	global_load_dword v201, v245, s[22:23] offset:0
	global_load_dword v202, v245, s[22:23] offset:64
	global_load_dword v203, v245, s[22:23] offset:128
	global_load_dword v204, v245, s[22:23] offset:192
	global_load_dword v205, v245, s[30:31] offset:0
	global_load_dword v206, v245, s[30:31] offset:64
	global_load_dword v207, v245, s[30:31] offset:128
	global_load_dword v208, v245, s[30:31] offset:192
	s_mov_b64 s[18:19], s[20:21]
	global_load_dword v129, v246, s[18:19] offset:0
	global_load_dword v130, v246, s[18:19] offset:64
	global_load_dword v131, v246, s[18:19] offset:128
	global_load_dword v132, v246, s[18:19] offset:192
	s_add_u32 s18, s18, 0x1000
	s_addc_u32 s19, s19, 0
	global_load_dword v133, v246, s[18:19] offset:0
	global_load_dword v134, v246, s[18:19] offset:64
	global_load_dword v135, v246, s[18:19] offset:128
	global_load_dword v136, v246, s[18:19] offset:192
	s_add_u32 s18, s18, 0x1000
	s_addc_u32 s19, s19, 0
	global_load_dword v137, v246, s[18:19] offset:0
	global_load_dword v138, v246, s[18:19] offset:64
	global_load_dword v139, v246, s[18:19] offset:128
	global_load_dword v140, v246, s[18:19] offset:192
	s_add_u32 s18, s18, 0x1000
	s_addc_u32 s19, s19, 0
	global_load_dword v141, v246, s[18:19] offset:0
	global_load_dword v142, v246, s[18:19] offset:64
	global_load_dword v143, v246, s[18:19] offset:128
	global_load_dword v144, v246, s[18:19] offset:192
	s_add_u32 s18, s18, 0xd000
	s_addc_u32 s19, s19, 0
	global_load_dword v145, v246, s[18:19] offset:0
	global_load_dword v146, v246, s[18:19] offset:64
	global_load_dword v147, v246, s[18:19] offset:128
	global_load_dword v148, v246, s[18:19] offset:192
	s_add_u32 s18, s18, 0x1000
	s_addc_u32 s19, s19, 0
	global_load_dword v149, v246, s[18:19] offset:0
	global_load_dword v150, v246, s[18:19] offset:64
	global_load_dword v151, v246, s[18:19] offset:128
	global_load_dword v152, v246, s[18:19] offset:192
	s_add_u32 s18, s18, 0x1000
	s_addc_u32 s19, s19, 0
	global_load_dword v153, v246, s[18:19] offset:0
	global_load_dword v154, v246, s[18:19] offset:64
	global_load_dword v155, v246, s[18:19] offset:128
	global_load_dword v156, v246, s[18:19] offset:192
	s_add_u32 s18, s18, 0x1000
	s_addc_u32 s19, s19, 0
	global_load_dword v157, v246, s[18:19] offset:0
	global_load_dword v158, v246, s[18:19] offset:64
	global_load_dword v159, v246, s[18:19] offset:128
	global_load_dword v160, v246, s[18:19] offset:192
	s_add_u32 s18, s18, 0xd000
	s_addc_u32 s19, s19, 0
	global_load_dword v161, v246, s[18:19] offset:0
	global_load_dword v170, v246, s[18:19] offset:64
	global_load_dword v171, v246, s[18:19] offset:128
	global_load_dword v172, v246, s[18:19] offset:192
	s_add_u32 s18, s18, 0x1000
	s_addc_u32 s19, s19, 0
	global_load_dword v173, v246, s[18:19] offset:0
	global_load_dword v174, v246, s[18:19] offset:64
	global_load_dword v175, v246, s[18:19] offset:128
	global_load_dword v176, v246, s[18:19] offset:192
	s_add_u32 s18, s18, 0x1000
	s_addc_u32 s19, s19, 0
	global_load_dword v177, v246, s[18:19] offset:0
	global_load_dword v178, v246, s[18:19] offset:64
	global_load_dword v179, v246, s[18:19] offset:128
	global_load_dword v180, v246, s[18:19] offset:192
	s_add_u32 s18, s18, 0x1000
	s_addc_u32 s19, s19, 0
	global_load_dword v181, v246, s[18:19] offset:0
	global_load_dword v182, v246, s[18:19] offset:64
	global_load_dword v183, v246, s[18:19] offset:128
	global_load_dword v184, v246, s[18:19] offset:192
	s_add_u32 s18, s18, 0xd000
	s_addc_u32 s19, s19, 0
	global_load_dword v185, v246, s[18:19] offset:0
	global_load_dword v186, v246, s[18:19] offset:64
	global_load_dword v187, v246, s[18:19] offset:128
	global_load_dword v188, v246, s[18:19] offset:192
	s_add_u32 s18, s18, 0x1000
	s_addc_u32 s19, s19, 0
	global_load_dword v189, v246, s[18:19] offset:0
	global_load_dword v190, v246, s[18:19] offset:64
	global_load_dword v191, v246, s[18:19] offset:128
	global_load_dword v192, v246, s[18:19] offset:192
	s_add_u32 s18, s18, 0x1000
	s_addc_u32 s19, s19, 0
	global_load_dword v193, v246, s[18:19] offset:0
	global_load_dword v194, v246, s[18:19] offset:64
	global_load_dword v195, v246, s[18:19] offset:128
	global_load_dword v196, v246, s[18:19] offset:192
	s_add_u32 s18, s18, 0x1000
	s_addc_u32 s19, s19, 0
	global_load_dword v197, v246, s[18:19] offset:0
	global_load_dword v198, v246, s[18:19] offset:64
	global_load_dword v199, v246, s[18:19] offset:128
	global_load_dword v200, v246, s[18:19] offset:192
	s_waitcnt vmcnt(63)
	s_barrier
	ds_read_b128 v[64:67], v252 offset:0
	ds_read_b128 v[96:99], v254 offset:32768
	ds_read_b128 v[100:103], v254 offset:34816
	ds_read_b128 v[104:107], v254 offset:36864
	ds_read_b128 v[108:111], v254 offset:38912
	ds_read_b128 v[68:71], v252 offset:2048
	ds_read_b128 v[72:75], v252 offset:4096
	ds_read_b128 v[76:79], v252 offset:6144
	ds_read_b128 v[80:83], v253 offset:0
	ds_read_b128 v[112:115], v255 offset:32768
	ds_read_b128 v[116:119], v255 offset:34816
	ds_read_b128 v[120:123], v255 offset:36864
	ds_read_b128 v[124:127], v255 offset:38912
	s_waitcnt lgkmcnt(11)
	v_mfma_f32_16x16x32_bf16 v[0:3], v[64:67], v[96:99], v[0:3]
	s_waitcnt lgkmcnt(10)
	v_mfma_f32_16x16x32_bf16 v[4:7], v[64:67], v[100:103], v[4:7]
	s_waitcnt lgkmcnt(9)
	v_mfma_f32_16x16x32_bf16 v[8:11], v[64:67], v[104:107], v[8:11]
	s_waitcnt lgkmcnt(8)
	v_mfma_f32_16x16x32_bf16 v[12:15], v[64:67], v[108:111], v[12:15]
	ds_read_b128 v[84:87], v253 offset:2048
	ds_read_b128 v[88:91], v253 offset:4096
	ds_read_b128 v[92:95], v253 offset:6144
	s_waitcnt lgkmcnt(10)
	v_mfma_f32_16x16x32_bf16 v[16:19], v[68:71], v[96:99], v[16:19]
	v_mfma_f32_16x16x32_bf16 v[20:23], v[68:71], v[100:103], v[20:23]
	v_mfma_f32_16x16x32_bf16 v[24:27], v[68:71], v[104:107], v[24:27]
	v_mfma_f32_16x16x32_bf16 v[28:31], v[68:71], v[108:111], v[28:31]
	s_waitcnt lgkmcnt(0)
	s_barrier
	s_add_u32 m0, s12, 0x0
	v_mfma_f32_16x16x32_bf16 v[32:35], v[72:75], v[96:99], v[32:35]
	global_load_lds_dwordx4 v248, s[8:9]
	s_add_u32 m0, s12, 0x400
	v_mfma_f32_16x16x32_bf16 v[36:39], v[72:75], v[100:103], v[36:39]
	global_load_lds_dwordx4 v249, s[8:9]
	s_add_u32 m0, s12, 0x800
	v_mfma_f32_16x16x32_bf16 v[40:43], v[72:75], v[104:107], v[40:43]
	global_load_lds_dwordx4 v250, s[8:9]
	s_add_u32 m0, s12, 0xc00
	v_mfma_f32_16x16x32_bf16 v[44:47], v[72:75], v[108:111], v[44:47]
	global_load_lds_dwordx4 v251, s[8:9]
	s_add_u32 m0, s12, 0x8000
	v_mfma_f32_16x16x32_bf16 v[48:51], v[76:79], v[96:99], v[48:51]
	global_load_lds_dwordx4 v248, s[10:11]
	s_add_u32 m0, s12, 0x8400
	v_mfma_f32_16x16x32_bf16 v[52:55], v[76:79], v[100:103], v[52:55]
	global_load_lds_dwordx4 v249, s[10:11]
	s_add_u32 m0, s12, 0x8800
	v_mfma_f32_16x16x32_bf16 v[56:59], v[76:79], v[104:107], v[56:59]
	global_load_lds_dwordx4 v250, s[10:11]
	s_add_u32 m0, s12, 0x8c00
	v_mfma_f32_16x16x32_bf16 v[60:63], v[76:79], v[108:111], v[60:63]
	global_load_lds_dwordx4 v251, s[10:11]
	s_add_u32 s8, s8, 0x80
	s_addc_u32 s9, s9, 0
	s_add_u32 s10, s10, 0x80
	s_addc_u32 s11, s11, 0
	s_waitcnt vmcnt(63)
	s_barrier
	ds_read_b128 v[64:67], v252 offset:16384
	ds_read_b128 v[96:99], v254 offset:49152
	ds_read_b128 v[100:103], v254 offset:51200
	ds_read_b128 v[104:107], v254 offset:53248
	ds_read_b128 v[108:111], v254 offset:55296
	ds_read_b128 v[68:71], v252 offset:18432
	ds_read_b128 v[72:75], v252 offset:20480
	ds_read_b128 v[76:79], v252 offset:22528
	v_mfma_f32_16x16x32_bf16 v[0:3], v[80:83], v[112:115], v[0:3]
	v_mfma_f32_16x16x32_bf16 v[4:7], v[80:83], v[116:119], v[4:7]
	v_mfma_f32_16x16x32_bf16 v[8:11], v[80:83], v[120:123], v[8:11]
	v_mfma_f32_16x16x32_bf16 v[12:15], v[80:83], v[124:127], v[12:15]
	v_mfma_f32_16x16x32_bf16 v[16:19], v[84:87], v[112:115], v[16:19]
	v_mfma_f32_16x16x32_bf16 v[20:23], v[84:87], v[116:119], v[20:23]
	v_mfma_f32_16x16x32_bf16 v[24:27], v[84:87], v[120:123], v[24:27]
	v_mfma_f32_16x16x32_bf16 v[28:31], v[84:87], v[124:127], v[28:31]
	v_mfma_f32_16x16x32_bf16 v[32:35], v[88:91], v[112:115], v[32:35]
	v_mfma_f32_16x16x32_bf16 v[36:39], v[88:91], v[116:119], v[36:39]
	v_mfma_f32_16x16x32_bf16 v[40:43], v[88:91], v[120:123], v[40:43]
	v_mfma_f32_16x16x32_bf16 v[44:47], v[88:91], v[124:127], v[44:47]
	v_mfma_f32_16x16x32_bf16 v[48:51], v[92:95], v[112:115], v[48:51]
	v_mfma_f32_16x16x32_bf16 v[52:55], v[92:95], v[116:119], v[52:55]
	v_mfma_f32_16x16x32_bf16 v[56:59], v[92:95], v[120:123], v[56:59]
	v_mfma_f32_16x16x32_bf16 v[60:63], v[92:95], v[124:127], v[60:63]
	ds_read_b128 v[80:83], v253 offset:16384
	ds_read_b128 v[112:115], v255 offset:49152
	ds_read_b128 v[116:119], v255 offset:51200
	ds_read_b128 v[120:123], v255 offset:53248
	ds_read_b128 v[124:127], v255 offset:55296
	ds_read_b128 v[84:87], v253 offset:18432
	ds_read_b128 v[88:91], v253 offset:20480
	ds_read_b128 v[92:95], v253 offset:22528
	s_waitcnt lgkmcnt(14)
	v_mfma_f32_16x16x32_bf16 v[0:3], v[64:67], v[96:99], v[0:3]
	s_waitcnt lgkmcnt(13)
	v_mfma_f32_16x16x32_bf16 v[4:7], v[64:67], v[100:103], v[4:7]
	s_waitcnt lgkmcnt(12)
	v_mfma_f32_16x16x32_bf16 v[8:11], v[64:67], v[104:107], v[8:11]
	s_waitcnt lgkmcnt(11)
	v_mfma_f32_16x16x32_bf16 v[12:15], v[64:67], v[108:111], v[12:15]
	s_waitcnt lgkmcnt(10)
	v_mfma_f32_16x16x32_bf16 v[16:19], v[68:71], v[96:99], v[16:19]
	v_mfma_f32_16x16x32_bf16 v[20:23], v[68:71], v[100:103], v[20:23]
	v_mfma_f32_16x16x32_bf16 v[24:27], v[68:71], v[104:107], v[24:27]
	v_mfma_f32_16x16x32_bf16 v[28:31], v[68:71], v[108:111], v[28:31]
	s_waitcnt lgkmcnt(0)
	s_barrier
	s_add_u32 m0, s12, 0x4000
	v_mfma_f32_16x16x32_bf16 v[32:35], v[72:75], v[96:99], v[32:35]
	global_load_lds_dwordx4 v248, s[8:9]
	s_add_u32 m0, s12, 0x4400
	v_mfma_f32_16x16x32_bf16 v[36:39], v[72:75], v[100:103], v[36:39]
	global_load_lds_dwordx4 v249, s[8:9]
	s_add_u32 m0, s12, 0x4800
	v_mfma_f32_16x16x32_bf16 v[40:43], v[72:75], v[104:107], v[40:43]
	global_load_lds_dwordx4 v250, s[8:9]
	s_add_u32 m0, s12, 0x4c00
	v_mfma_f32_16x16x32_bf16 v[44:47], v[72:75], v[108:111], v[44:47]
	global_load_lds_dwordx4 v251, s[8:9]
	s_add_u32 m0, s12, 0xc000
	v_mfma_f32_16x16x32_bf16 v[48:51], v[76:79], v[96:99], v[48:51]
	global_load_lds_dwordx4 v248, s[10:11]
	s_add_u32 m0, s12, 0xc400
	v_mfma_f32_16x16x32_bf16 v[52:55], v[76:79], v[100:103], v[52:55]
	global_load_lds_dwordx4 v249, s[10:11]
	s_add_u32 m0, s12, 0xc800
	v_mfma_f32_16x16x32_bf16 v[56:59], v[76:79], v[104:107], v[56:59]
	global_load_lds_dwordx4 v250, s[10:11]
	s_add_u32 m0, s12, 0xcc00
	v_mfma_f32_16x16x32_bf16 v[60:63], v[76:79], v[108:111], v[60:63]
	global_load_lds_dwordx4 v251, s[10:11]
	s_add_u32 s8, s8, 0x80
	s_addc_u32 s9, s9, 0
	s_add_u32 s10, s10, 0x80
	s_addc_u32 s11, s11, 0
	s_mov_b32 s13, 6

.Lr32_tile:
	s_cmp_lt_u32 s15, 0x200
	s_cbranch_scc0 .Lr32_end
	s_and_b32 s2, s15, 63
	s_lshr_b32 s3, s15, 6
	s_mul_i32 s14, s2, 0xb0000
	s_add_u32 s8, s26, s14
	s_addc_u32 s9, s27, 0
	s_mul_i32 s14, s3, 0xb0000
	s_add_u32 s10, s28, s14
	s_addc_u32 s11, s29, 0
	s_lshl_b32 s14, s2, 19
	s_lshl_b32 s6, s3, 9
	s_add_u32 s14, s14, s6
	s_add_u32 s20, s4, 0x6b7a100
	s_addc_u32 s21, s5, 0
	s_add_u32 s20, s20, s14
	s_addc_u32 s21, s21, 0
	s_sub_u32 s7, s2, 32
	s_lshr_b32 s7, s7, 3
	s_add_u32 s7, s7, 1
	s_cmp_lt_u32 s2, 32
	s_cselect_b32 s7, 0, s7
	s_mul_i32 s7, s7, 0x6000
	s_add_u32 s7, s7, s6
	s_add_u32 s22, s4, 0x6b61000
	s_addc_u32 s23, s5, 0
	s_add_u32 s22, s22, s7
	s_addc_u32 s23, s23, 0
	v_readfirstlane_b32 s12, v247
	s_lshl_b32 s12, s12, 12
	s_add_u32 m0, s12, 0x0
	v_mov_b32_e32 v0, 0
	global_load_lds_dwordx4 v248, s[8:9]
	v_mov_b32_e32 v1, 0
	s_add_u32 m0, s12, 0x400
	v_mov_b32_e32 v2, 0
	global_load_lds_dwordx4 v249, s[8:9]
	v_mov_b32_e32 v3, 0
	s_add_u32 m0, s12, 0x800
	v_mov_b32_e32 v4, 0
	global_load_lds_dwordx4 v250, s[8:9]
	v_mov_b32_e32 v5, 0
	s_add_u32 m0, s12, 0xc00
	v_mov_b32_e32 v6, 0
	global_load_lds_dwordx4 v251, s[8:9]
	v_mov_b32_e32 v7, 0
	s_add_u32 m0, s12, 0x8000
	v_mov_b32_e32 v8, 0
	global_load_lds_dwordx4 v248, s[10:11]
	v_mov_b32_e32 v9, 0
	s_add_u32 m0, s12, 0x8400
	v_mov_b32_e32 v10, 0
	global_load_lds_dwordx4 v249, s[10:11]
	v_mov_b32_e32 v11, 0
	s_add_u32 m0, s12, 0x8800
	v_mov_b32_e32 v12, 0
	global_load_lds_dwordx4 v250, s[10:11]
	v_mov_b32_e32 v13, 0
	s_add_u32 m0, s12, 0x8c00
	v_mov_b32_e32 v14, 0
	global_load_lds_dwordx4 v251, s[10:11]
	v_mov_b32_e32 v15, 0
	s_add_u32 s8, s8, 0x80
	s_addc_u32 s9, s9, 0
	s_add_u32 s10, s10, 0x80
	s_addc_u32 s11, s11, 0
	s_add_u32 m0, s12, 0x4000
	v_mov_b32_e32 v16, 0
	global_load_lds_dwordx4 v248, s[8:9]
	v_mov_b32_e32 v17, 0
	s_add_u32 m0, s12, 0x4400
	v_mov_b32_e32 v18, 0
	global_load_lds_dwordx4 v249, s[8:9]
	v_mov_b32_e32 v19, 0
	s_add_u32 m0, s12, 0x4800
	v_mov_b32_e32 v20, 0
	global_load_lds_dwordx4 v250, s[8:9]
	v_mov_b32_e32 v21, 0
	s_add_u32 m0, s12, 0x4c00
	v_mov_b32_e32 v22, 0
	global_load_lds_dwordx4 v251, s[8:9]
	v_mov_b32_e32 v23, 0
	s_add_u32 m0, s12, 0xc000
	v_mov_b32_e32 v24, 0
	global_load_lds_dwordx4 v248, s[10:11]
	v_mov_b32_e32 v25, 0
	s_add_u32 m0, s12, 0xc400
	v_mov_b32_e32 v26, 0
	global_load_lds_dwordx4 v249, s[10:11]
	v_mov_b32_e32 v27, 0
	s_add_u32 m0, s12, 0xc800
	v_mov_b32_e32 v28, 0
	global_load_lds_dwordx4 v250, s[10:11]
	v_mov_b32_e32 v29, 0
	s_add_u32 m0, s12, 0xcc00
	v_mov_b32_e32 v30, 0
	global_load_lds_dwordx4 v251, s[10:11]
	v_mov_b32_e32 v31, 0
	s_add_u32 s8, s8, 0x80
	s_addc_u32 s9, s9, 0
	s_add_u32 s10, s10, 0x80
	s_addc_u32 s11, s11, 0
	v_mov_b32_e32 v32, 0
	v_mov_b32_e32 v33, 0
	v_mov_b32_e32 v34, 0
	v_mov_b32_e32 v35, 0
	v_mov_b32_e32 v36, 0
	v_mov_b32_e32 v37, 0
	v_mov_b32_e32 v38, 0
	v_mov_b32_e32 v39, 0
	v_mov_b32_e32 v40, 0
	v_mov_b32_e32 v41, 0
	v_mov_b32_e32 v42, 0
	v_mov_b32_e32 v43, 0
	v_mov_b32_e32 v44, 0
	v_mov_b32_e32 v45, 0
	v_mov_b32_e32 v46, 0
	v_mov_b32_e32 v47, 0
	v_mov_b32_e32 v48, 0
	v_mov_b32_e32 v49, 0
	v_mov_b32_e32 v50, 0
	v_mov_b32_e32 v51, 0
	v_mov_b32_e32 v52, 0
	v_mov_b32_e32 v53, 0
	v_mov_b32_e32 v54, 0
	v_mov_b32_e32 v55, 0
	v_mov_b32_e32 v56, 0
	v_mov_b32_e32 v57, 0
	v_mov_b32_e32 v58, 0
	v_mov_b32_e32 v59, 0
	v_mov_b32_e32 v60, 0
	v_mov_b32_e32 v61, 0
	v_mov_b32_e32 v62, 0
	v_mov_b32_e32 v63, 0
	global_load_dword v201, v245, s[22:23] offset:0
	global_load_dword v202, v245, s[22:23] offset:64
	global_load_dword v203, v245, s[22:23] offset:128
	global_load_dword v204, v245, s[22:23] offset:192
	s_mov_b64 s[18:19], s[20:21]
	global_load_dword v129, v246, s[18:19] offset:0
	global_load_dword v130, v246, s[18:19] offset:64
	global_load_dword v131, v246, s[18:19] offset:128
	global_load_dword v132, v246, s[18:19] offset:192
	s_add_u32 s18, s18, 0x1000
	s_addc_u32 s19, s19, 0
	global_load_dword v133, v246, s[18:19] offset:0
	global_load_dword v134, v246, s[18:19] offset:64
	global_load_dword v135, v246, s[18:19] offset:128
	global_load_dword v136, v246, s[18:19] offset:192
	s_add_u32 s18, s18, 0x1000
	s_addc_u32 s19, s19, 0
	global_load_dword v137, v246, s[18:19] offset:0
	global_load_dword v138, v246, s[18:19] offset:64
	global_load_dword v139, v246, s[18:19] offset:128
	global_load_dword v140, v246, s[18:19] offset:192
	s_add_u32 s18, s18, 0x1000
	s_addc_u32 s19, s19, 0
	global_load_dword v141, v246, s[18:19] offset:0
	global_load_dword v142, v246, s[18:19] offset:64
	global_load_dword v143, v246, s[18:19] offset:128
	global_load_dword v144, v246, s[18:19] offset:192
	s_add_u32 s18, s18, 0xd000
	s_addc_u32 s19, s19, 0
	global_load_dword v145, v246, s[18:19] offset:0
	global_load_dword v146, v246, s[18:19] offset:64
	global_load_dword v147, v246, s[18:19] offset:128
	global_load_dword v148, v246, s[18:19] offset:192
	s_add_u32 s18, s18, 0x1000
	s_addc_u32 s19, s19, 0
	global_load_dword v149, v246, s[18:19] offset:0
	global_load_dword v150, v246, s[18:19] offset:64
	global_load_dword v151, v246, s[18:19] offset:128
	global_load_dword v152, v246, s[18:19] offset:192
	s_add_u32 s18, s18, 0x1000
	s_addc_u32 s19, s19, 0
	global_load_dword v153, v246, s[18:19] offset:0
	global_load_dword v154, v246, s[18:19] offset:64
	global_load_dword v155, v246, s[18:19] offset:128
	global_load_dword v156, v246, s[18:19] offset:192
	s_add_u32 s18, s18, 0x1000
	s_addc_u32 s19, s19, 0
	global_load_dword v157, v246, s[18:19] offset:0
	global_load_dword v158, v246, s[18:19] offset:64
	global_load_dword v159, v246, s[18:19] offset:128
	global_load_dword v160, v246, s[18:19] offset:192
	s_add_u32 s18, s18, 0xd000
	s_addc_u32 s19, s19, 0
	global_load_dword v161, v246, s[18:19] offset:0
	global_load_dword v170, v246, s[18:19] offset:64
	global_load_dword v171, v246, s[18:19] offset:128
	global_load_dword v172, v246, s[18:19] offset:192
	s_add_u32 s18, s18, 0x1000
	s_addc_u32 s19, s19, 0
	global_load_dword v173, v246, s[18:19] offset:0
	global_load_dword v174, v246, s[18:19] offset:64
	global_load_dword v175, v246, s[18:19] offset:128
	global_load_dword v176, v246, s[18:19] offset:192
	s_add_u32 s18, s18, 0x1000
	s_addc_u32 s19, s19, 0
	global_load_dword v177, v246, s[18:19] offset:0
	global_load_dword v178, v246, s[18:19] offset:64
	global_load_dword v179, v246, s[18:19] offset:128
	global_load_dword v180, v246, s[18:19] offset:192
	s_add_u32 s18, s18, 0x1000
	s_addc_u32 s19, s19, 0
	global_load_dword v181, v246, s[18:19] offset:0
	global_load_dword v182, v246, s[18:19] offset:64
	global_load_dword v183, v246, s[18:19] offset:128
	global_load_dword v184, v246, s[18:19] offset:192
	s_add_u32 s18, s18, 0xd000
	s_addc_u32 s19, s19, 0
	global_load_dword v185, v246, s[18:19] offset:0
	global_load_dword v186, v246, s[18:19] offset:64
	global_load_dword v187, v246, s[18:19] offset:128
	global_load_dword v188, v246, s[18:19] offset:192
	s_add_u32 s18, s18, 0x1000
	s_addc_u32 s19, s19, 0
	global_load_dword v189, v246, s[18:19] offset:0
	global_load_dword v190, v246, s[18:19] offset:64
	global_load_dword v191, v246, s[18:19] offset:128
	global_load_dword v192, v246, s[18:19] offset:192
	s_add_u32 s18, s18, 0x1000
	s_addc_u32 s19, s19, 0
	global_load_dword v193, v246, s[18:19] offset:0
	global_load_dword v194, v246, s[18:19] offset:64
	global_load_dword v195, v246, s[18:19] offset:128
	global_load_dword v196, v246, s[18:19] offset:192
	s_add_u32 s18, s18, 0x1000
	s_addc_u32 s19, s19, 0
	global_load_dword v197, v246, s[18:19] offset:0
	global_load_dword v198, v246, s[18:19] offset:64
	global_load_dword v199, v246, s[18:19] offset:128
	global_load_dword v200, v246, s[18:19] offset:192
	s_waitcnt vmcnt(63)
	s_barrier
	ds_read_b128 v[64:67], v252 offset:0
	ds_read_b128 v[96:99], v254 offset:32768
	ds_read_b128 v[100:103], v254 offset:34816
	ds_read_b128 v[104:107], v254 offset:36864
	ds_read_b128 v[108:111], v254 offset:38912
	ds_read_b128 v[68:71], v252 offset:2048
	ds_read_b128 v[72:75], v252 offset:4096
	ds_read_b128 v[76:79], v252 offset:6144
	ds_read_b128 v[80:83], v253 offset:0
	ds_read_b128 v[112:115], v255 offset:32768
	ds_read_b128 v[116:119], v255 offset:34816
	ds_read_b128 v[120:123], v255 offset:36864
	ds_read_b128 v[124:127], v255 offset:38912
	s_waitcnt lgkmcnt(11)
	v_mfma_f32_16x16x32_bf16 v[0:3], v[64:67], v[96:99], v[0:3]
	s_waitcnt lgkmcnt(10)
	v_mfma_f32_16x16x32_bf16 v[4:7], v[64:67], v[100:103], v[4:7]
	s_waitcnt lgkmcnt(9)
	v_mfma_f32_16x16x32_bf16 v[8:11], v[64:67], v[104:107], v[8:11]
	s_waitcnt lgkmcnt(8)
	v_mfma_f32_16x16x32_bf16 v[12:15], v[64:67], v[108:111], v[12:15]
	ds_read_b128 v[84:87], v253 offset:2048
	ds_read_b128 v[88:91], v253 offset:4096
	ds_read_b128 v[92:95], v253 offset:6144
	s_waitcnt lgkmcnt(10)
	v_mfma_f32_16x16x32_bf16 v[16:19], v[68:71], v[96:99], v[16:19]
	v_mfma_f32_16x16x32_bf16 v[20:23], v[68:71], v[100:103], v[20:23]
	v_mfma_f32_16x16x32_bf16 v[24:27], v[68:71], v[104:107], v[24:27]
	v_mfma_f32_16x16x32_bf16 v[28:31], v[68:71], v[108:111], v[28:31]
	s_waitcnt lgkmcnt(0)
	s_barrier
	s_add_u32 m0, s12, 0x0
	v_mfma_f32_16x16x32_bf16 v[32:35], v[72:75], v[96:99], v[32:35]
	global_load_lds_dwordx4 v248, s[8:9]
	s_add_u32 m0, s12, 0x400
	v_mfma_f32_16x16x32_bf16 v[36:39], v[72:75], v[100:103], v[36:39]
	global_load_lds_dwordx4 v249, s[8:9]
	s_add_u32 m0, s12, 0x800
	v_mfma_f32_16x16x32_bf16 v[40:43], v[72:75], v[104:107], v[40:43]
	global_load_lds_dwordx4 v250, s[8:9]
	s_add_u32 m0, s12, 0xc00
	v_mfma_f32_16x16x32_bf16 v[44:47], v[72:75], v[108:111], v[44:47]
	global_load_lds_dwordx4 v251, s[8:9]
	s_add_u32 m0, s12, 0x8000
	v_mfma_f32_16x16x32_bf16 v[48:51], v[76:79], v[96:99], v[48:51]
	global_load_lds_dwordx4 v248, s[10:11]
	s_add_u32 m0, s12, 0x8400
	v_mfma_f32_16x16x32_bf16 v[52:55], v[76:79], v[100:103], v[52:55]
	global_load_lds_dwordx4 v249, s[10:11]
	s_add_u32 m0, s12, 0x8800
	v_mfma_f32_16x16x32_bf16 v[56:59], v[76:79], v[104:107], v[56:59]
	global_load_lds_dwordx4 v250, s[10:11]
	s_add_u32 m0, s12, 0x8c00
	v_mfma_f32_16x16x32_bf16 v[60:63], v[76:79], v[108:111], v[60:63]
	global_load_lds_dwordx4 v251, s[10:11]
	s_add_u32 s8, s8, 0x80
	s_addc_u32 s9, s9, 0
	s_add_u32 s10, s10, 0x80
	s_addc_u32 s11, s11, 0
	s_waitcnt vmcnt(63)
	s_barrier
	ds_read_b128 v[64:67], v252 offset:16384
	ds_read_b128 v[96:99], v254 offset:49152
	ds_read_b128 v[100:103], v254 offset:51200
	ds_read_b128 v[104:107], v254 offset:53248
	ds_read_b128 v[108:111], v254 offset:55296
	ds_read_b128 v[68:71], v252 offset:18432
	ds_read_b128 v[72:75], v252 offset:20480
	ds_read_b128 v[76:79], v252 offset:22528
	v_mfma_f32_16x16x32_bf16 v[0:3], v[80:83], v[112:115], v[0:3]
	v_mfma_f32_16x16x32_bf16 v[4:7], v[80:83], v[116:119], v[4:7]
	v_mfma_f32_16x16x32_bf16 v[8:11], v[80:83], v[120:123], v[8:11]
	v_mfma_f32_16x16x32_bf16 v[12:15], v[80:83], v[124:127], v[12:15]
	v_mfma_f32_16x16x32_bf16 v[16:19], v[84:87], v[112:115], v[16:19]
	v_mfma_f32_16x16x32_bf16 v[20:23], v[84:87], v[116:119], v[20:23]
	v_mfma_f32_16x16x32_bf16 v[24:27], v[84:87], v[120:123], v[24:27]
	v_mfma_f32_16x16x32_bf16 v[28:31], v[84:87], v[124:127], v[28:31]
	v_mfma_f32_16x16x32_bf16 v[32:35], v[88:91], v[112:115], v[32:35]
	v_mfma_f32_16x16x32_bf16 v[36:39], v[88:91], v[116:119], v[36:39]
	v_mfma_f32_16x16x32_bf16 v[40:43], v[88:91], v[120:123], v[40:43]
	v_mfma_f32_16x16x32_bf16 v[44:47], v[88:91], v[124:127], v[44:47]
	v_mfma_f32_16x16x32_bf16 v[48:51], v[92:95], v[112:115], v[48:51]
	v_mfma_f32_16x16x32_bf16 v[52:55], v[92:95], v[116:119], v[52:55]
	v_mfma_f32_16x16x32_bf16 v[56:59], v[92:95], v[120:123], v[56:59]
	v_mfma_f32_16x16x32_bf16 v[60:63], v[92:95], v[124:127], v[60:63]
	ds_read_b128 v[80:83], v253 offset:16384
	ds_read_b128 v[112:115], v255 offset:49152
	ds_read_b128 v[116:119], v255 offset:51200
	ds_read_b128 v[120:123], v255 offset:53248
	ds_read_b128 v[124:127], v255 offset:55296
	ds_read_b128 v[84:87], v253 offset:18432
	ds_read_b128 v[88:91], v253 offset:20480
	ds_read_b128 v[92:95], v253 offset:22528
	s_waitcnt lgkmcnt(14)
	v_mfma_f32_16x16x32_bf16 v[0:3], v[64:67], v[96:99], v[0:3]
	s_waitcnt lgkmcnt(13)
	v_mfma_f32_16x16x32_bf16 v[4:7], v[64:67], v[100:103], v[4:7]
	s_waitcnt lgkmcnt(12)
	v_mfma_f32_16x16x32_bf16 v[8:11], v[64:67], v[104:107], v[8:11]
	s_waitcnt lgkmcnt(11)
	v_mfma_f32_16x16x32_bf16 v[12:15], v[64:67], v[108:111], v[12:15]
	s_waitcnt lgkmcnt(10)
	v_mfma_f32_16x16x32_bf16 v[16:19], v[68:71], v[96:99], v[16:19]
	v_mfma_f32_16x16x32_bf16 v[20:23], v[68:71], v[100:103], v[20:23]
	v_mfma_f32_16x16x32_bf16 v[24:27], v[68:71], v[104:107], v[24:27]
	v_mfma_f32_16x16x32_bf16 v[28:31], v[68:71], v[108:111], v[28:31]
	s_waitcnt lgkmcnt(0)
	s_barrier
	s_add_u32 m0, s12, 0x4000
	v_mfma_f32_16x16x32_bf16 v[32:35], v[72:75], v[96:99], v[32:35]
	global_load_lds_dwordx4 v248, s[8:9]
	s_add_u32 m0, s12, 0x4400
	v_mfma_f32_16x16x32_bf16 v[36:39], v[72:75], v[100:103], v[36:39]
	global_load_lds_dwordx4 v249, s[8:9]
	s_add_u32 m0, s12, 0x4800
	v_mfma_f32_16x16x32_bf16 v[40:43], v[72:75], v[104:107], v[40:43]
	global_load_lds_dwordx4 v250, s[8:9]
	s_add_u32 m0, s12, 0x4c00
	v_mfma_f32_16x16x32_bf16 v[44:47], v[72:75], v[108:111], v[44:47]
	global_load_lds_dwordx4 v251, s[8:9]
	s_add_u32 m0, s12, 0xc000
	v_mfma_f32_16x16x32_bf16 v[48:51], v[76:79], v[96:99], v[48:51]
	global_load_lds_dwordx4 v248, s[10:11]
	s_add_u32 m0, s12, 0xc400
	v_mfma_f32_16x16x32_bf16 v[52:55], v[76:79], v[100:103], v[52:55]
	global_load_lds_dwordx4 v249, s[10:11]
	s_add_u32 m0, s12, 0xc800
	v_mfma_f32_16x16x32_bf16 v[56:59], v[76:79], v[104:107], v[56:59]
	global_load_lds_dwordx4 v250, s[10:11]
	s_add_u32 m0, s12, 0xcc00
	v_mfma_f32_16x16x32_bf16 v[60:63], v[76:79], v[108:111], v[60:63]
	global_load_lds_dwordx4 v251, s[10:11]
	s_add_u32 s8, s8, 0x80
	s_addc_u32 s9, s9, 0
	s_add_u32 s10, s10, 0x80
	s_addc_u32 s11, s11, 0
	s_mov_b32 s13, 20
